# FFN_IN SwiGLU epilogue rewritten with packed-f32 VALU ops (v_pk_mul/add_f32), same op order, fewer issue slots
# speedup vs baseline: 1.0069x; 1.0069x over previous
.LBB0_582:
	s_waitcnt vmcnt(6)
	v_readlane_b32 s14, v255, 18
	v_readlane_b32 s15, v255, 19
	v_lshl_or_b32 v2, s22, 7, v221
	v_lshl_add_u32 v1, s20, 8, v219
	v_ashrrev_i32_e32 v3, 31, v2
	v_mov_b64_e32 v[140:141], s[14:15]
	v_mov_b32_e32 v136, 0xbfb8aa3b
	v_mov_b32_e32 v138, 1.0
	v_lshlrev_b64 v[2:3], 1, v[2:3]
	v_fmamk_f32 v132, v233, 0x3a800000, v226
	v_mul_f32_e32 v133, 0x4b800000, v132
	v_cmp_gt_f32_e32 vcc, s48, v132
	v_mad_i64_i32 v[144:145], s[14:15], v1, s49, v[140:141]
	v_lshl_add_u64 v[146:147], v[144:145], 0, v[2:3]
	v_cndmask_b32_e32 v132, v132, v133, vcc
	v_rsq_f32_e32 v132, v132
	s_nop 0
	v_mul_f32_e32 v133, 0x45800000, v132
	v_cndmask_b32_e32 v134, v132, v133, vcc
	v_pk_mul_f32 v[124:125], v[134:135], v[124:125] op_sel_hi:[0,1]
	v_pk_mul_f32 v[126:127], v[134:135], v[126:127] op_sel_hi:[0,1]
	v_pk_mul_f32 v[116:117], v[134:135], v[116:117] op_sel_hi:[0,1]
	v_pk_mul_f32 v[118:119], v[134:135], v[118:119] op_sel_hi:[0,1]
	v_pk_mul_f32 v[128:129], v[134:135], v[128:129] op_sel_hi:[0,1]
	v_pk_mul_f32 v[130:131], v[134:135], v[130:131] op_sel_hi:[0,1]
	v_pk_mul_f32 v[120:121], v[134:135], v[120:121] op_sel_hi:[0,1]
	v_pk_mul_f32 v[122:123], v[134:135], v[122:123] op_sel_hi:[0,1]
	v_pk_mul_f32 v[148:149], v[136:137], v[124:125] op_sel_hi:[0,1]
	v_pk_mul_f32 v[150:151], v[136:137], v[126:127] op_sel_hi:[0,1]
	v_pk_mul_f32 v[152:153], v[136:137], v[116:117] op_sel_hi:[0,1]
	v_pk_mul_f32 v[154:155], v[136:137], v[118:119] op_sel_hi:[0,1]
	v_exp_f32_e32 v148, v148
	v_exp_f32_e32 v149, v149
	v_exp_f32_e32 v150, v150
	v_exp_f32_e32 v151, v151
	v_exp_f32_e32 v152, v152
	v_exp_f32_e32 v153, v153
	v_exp_f32_e32 v154, v154
	v_exp_f32_e32 v155, v155
	v_fmamk_f32 v172, v232, 0x3a800000, v226
	v_or_b32_e32 v176, 16, v1
	v_mul_f32_e32 v173, 0x4b800000, v172
	v_cmp_gt_f32_e32 vcc, s48, v172
	v_mad_i64_i32 v[178:179], s[14:15], v176, s49, v[140:141]
	v_lshl_add_u64 v[180:181], v[178:179], 0, v[2:3]
	v_cndmask_b32_e32 v172, v172, v173, vcc
	v_rsq_f32_e32 v172, v172
	s_nop 0
	v_mul_f32_e32 v173, 0x45800000, v172
	v_cndmask_b32_e32 v174, v172, v173, vcc
	v_pk_add_f32 v[148:149], v[138:139], v[148:149] op_sel_hi:[0,1]
	v_pk_add_f32 v[150:151], v[138:139], v[150:151] op_sel_hi:[0,1]
	v_pk_add_f32 v[152:153], v[138:139], v[152:153] op_sel_hi:[0,1]
	v_pk_add_f32 v[154:155], v[138:139], v[154:155] op_sel_hi:[0,1]
	v_rcp_f32_e32 v148, v148
	v_rcp_f32_e32 v149, v149
	v_rcp_f32_e32 v150, v150
	v_rcp_f32_e32 v151, v151
	v_rcp_f32_e32 v152, v152
	v_rcp_f32_e32 v153, v153
	v_rcp_f32_e32 v154, v154
	v_rcp_f32_e32 v155, v155
	v_pk_mul_f32 v[148:149], v[124:125], v[148:149]
	v_pk_mul_f32 v[150:151], v[126:127], v[150:151]
	v_pk_mul_f32 v[152:153], v[116:117], v[152:153]
	v_pk_mul_f32 v[154:155], v[118:119], v[154:155]
	v_pk_mul_f32 v[128:129], v[128:129], v[148:149]
	v_pk_mul_f32 v[130:131], v[130:131], v[150:151]
	v_pk_mul_f32 v[120:121], v[120:121], v[152:153]
	v_pk_mul_f32 v[122:123], v[122:123], v[154:155]
	v_cvt_pk_bf16_f32 v156, v128, v129
	v_cvt_pk_bf16_f32 v157, v130, v131
	v_cvt_pk_bf16_f32 v158, v120, v121
	v_cvt_pk_bf16_f32 v159, v122, v123
	global_store_dwordx4 v[146:147], v[156:159], off
	v_pk_mul_f32 v[108:109], v[174:175], v[108:109] op_sel_hi:[0,1]
	v_pk_mul_f32 v[110:111], v[174:175], v[110:111] op_sel_hi:[0,1]
	v_pk_mul_f32 v[100:101], v[174:175], v[100:101] op_sel_hi:[0,1]
	v_pk_mul_f32 v[102:103], v[174:175], v[102:103] op_sel_hi:[0,1]
	v_pk_mul_f32 v[112:113], v[174:175], v[112:113] op_sel_hi:[0,1]
	v_pk_mul_f32 v[114:115], v[174:175], v[114:115] op_sel_hi:[0,1]
	v_pk_mul_f32 v[104:105], v[174:175], v[104:105] op_sel_hi:[0,1]
	v_pk_mul_f32 v[106:107], v[174:175], v[106:107] op_sel_hi:[0,1]
	v_pk_mul_f32 v[160:161], v[136:137], v[108:109] op_sel_hi:[0,1]
	v_pk_mul_f32 v[162:163], v[136:137], v[110:111] op_sel_hi:[0,1]
	v_pk_mul_f32 v[164:165], v[136:137], v[100:101] op_sel_hi:[0,1]
	v_pk_mul_f32 v[166:167], v[136:137], v[102:103] op_sel_hi:[0,1]
	v_exp_f32_e32 v160, v160
	v_exp_f32_e32 v161, v161
	v_exp_f32_e32 v162, v162
	v_exp_f32_e32 v163, v163
	v_exp_f32_e32 v164, v164
	v_exp_f32_e32 v165, v165
	v_exp_f32_e32 v166, v166
	v_exp_f32_e32 v167, v167
	v_fmamk_f32 v132, v231, 0x3a800000, v226
	v_or_b32_e32 v142, 32, v1
	v_mul_f32_e32 v133, 0x4b800000, v132
	v_cmp_gt_f32_e32 vcc, s48, v132
	v_mad_i64_i32 v[144:145], s[14:15], v142, s49, v[140:141]
	v_lshl_add_u64 v[146:147], v[144:145], 0, v[2:3]
	v_cndmask_b32_e32 v132, v132, v133, vcc
	v_rsq_f32_e32 v132, v132
	s_nop 0
	v_mul_f32_e32 v133, 0x45800000, v132
	v_cndmask_b32_e32 v134, v132, v133, vcc
	v_pk_add_f32 v[160:161], v[138:139], v[160:161] op_sel_hi:[0,1]
	v_pk_add_f32 v[162:163], v[138:139], v[162:163] op_sel_hi:[0,1]
	v_pk_add_f32 v[164:165], v[138:139], v[164:165] op_sel_hi:[0,1]
	v_pk_add_f32 v[166:167], v[138:139], v[166:167] op_sel_hi:[0,1]
	v_rcp_f32_e32 v160, v160
	v_rcp_f32_e32 v161, v161
	v_rcp_f32_e32 v162, v162
	v_rcp_f32_e32 v163, v163
	v_rcp_f32_e32 v164, v164
	v_rcp_f32_e32 v165, v165
	v_rcp_f32_e32 v166, v166
	v_rcp_f32_e32 v167, v167
	v_pk_mul_f32 v[160:161], v[108:109], v[160:161]
	v_pk_mul_f32 v[162:163], v[110:111], v[162:163]
	v_pk_mul_f32 v[164:165], v[100:101], v[164:165]
	v_pk_mul_f32 v[166:167], v[102:103], v[166:167]
	v_pk_mul_f32 v[112:113], v[112:113], v[160:161]
	v_pk_mul_f32 v[114:115], v[114:115], v[162:163]
	v_pk_mul_f32 v[104:105], v[104:105], v[164:165]
	v_pk_mul_f32 v[106:107], v[106:107], v[166:167]
	v_cvt_pk_bf16_f32 v168, v112, v113
	v_cvt_pk_bf16_f32 v169, v114, v115
	v_cvt_pk_bf16_f32 v170, v104, v105
	v_cvt_pk_bf16_f32 v171, v106, v107
	global_store_dwordx4 v[180:181], v[168:171], off
	v_pk_mul_f32 v[92:93], v[134:135], v[92:93] op_sel_hi:[0,1]
	v_pk_mul_f32 v[94:95], v[134:135], v[94:95] op_sel_hi:[0,1]
	v_pk_mul_f32 v[84:85], v[134:135], v[84:85] op_sel_hi:[0,1]
	v_pk_mul_f32 v[86:87], v[134:135], v[86:87] op_sel_hi:[0,1]
	v_pk_mul_f32 v[96:97], v[134:135], v[96:97] op_sel_hi:[0,1]
	v_pk_mul_f32 v[98:99], v[134:135], v[98:99] op_sel_hi:[0,1]
	v_pk_mul_f32 v[88:89], v[134:135], v[88:89] op_sel_hi:[0,1]
	v_pk_mul_f32 v[90:91], v[134:135], v[90:91] op_sel_hi:[0,1]
	v_pk_mul_f32 v[148:149], v[136:137], v[92:93] op_sel_hi:[0,1]
	v_pk_mul_f32 v[150:151], v[136:137], v[94:95] op_sel_hi:[0,1]
	v_pk_mul_f32 v[152:153], v[136:137], v[84:85] op_sel_hi:[0,1]
	v_pk_mul_f32 v[154:155], v[136:137], v[86:87] op_sel_hi:[0,1]
	v_exp_f32_e32 v148, v148
	v_exp_f32_e32 v149, v149
	v_exp_f32_e32 v150, v150
	v_exp_f32_e32 v151, v151
	v_exp_f32_e32 v152, v152
	v_exp_f32_e32 v153, v153
	v_exp_f32_e32 v154, v154
	v_exp_f32_e32 v155, v155
	v_fmamk_f32 v172, v230, 0x3a800000, v226
	v_or_b32_e32 v176, 48, v1
	v_mul_f32_e32 v173, 0x4b800000, v172
	v_cmp_gt_f32_e32 vcc, s48, v172
	v_mad_i64_i32 v[178:179], s[14:15], v176, s49, v[140:141]
	v_lshl_add_u64 v[180:181], v[178:179], 0, v[2:3]
	v_cndmask_b32_e32 v172, v172, v173, vcc
	v_rsq_f32_e32 v172, v172
	s_nop 0
	v_mul_f32_e32 v173, 0x45800000, v172
	v_cndmask_b32_e32 v174, v172, v173, vcc
	v_pk_add_f32 v[148:149], v[138:139], v[148:149] op_sel_hi:[0,1]
	v_pk_add_f32 v[150:151], v[138:139], v[150:151] op_sel_hi:[0,1]
	v_pk_add_f32 v[152:153], v[138:139], v[152:153] op_sel_hi:[0,1]
	v_pk_add_f32 v[154:155], v[138:139], v[154:155] op_sel_hi:[0,1]
	v_rcp_f32_e32 v148, v148
	v_rcp_f32_e32 v149, v149
	v_rcp_f32_e32 v150, v150
	v_rcp_f32_e32 v151, v151
	v_rcp_f32_e32 v152, v152
	v_rcp_f32_e32 v153, v153
	v_rcp_f32_e32 v154, v154
	v_rcp_f32_e32 v155, v155
	v_pk_mul_f32 v[148:149], v[92:93], v[148:149]
	v_pk_mul_f32 v[150:151], v[94:95], v[150:151]
	v_pk_mul_f32 v[152:153], v[84:85], v[152:153]
	v_pk_mul_f32 v[154:155], v[86:87], v[154:155]
	v_pk_mul_f32 v[96:97], v[96:97], v[148:149]
	v_pk_mul_f32 v[98:99], v[98:99], v[150:151]
	v_pk_mul_f32 v[88:89], v[88:89], v[152:153]
	v_pk_mul_f32 v[90:91], v[90:91], v[154:155]
	v_cvt_pk_bf16_f32 v156, v96, v97
	v_cvt_pk_bf16_f32 v157, v98, v99
	v_cvt_pk_bf16_f32 v158, v88, v89
	v_cvt_pk_bf16_f32 v159, v90, v91
	global_store_dwordx4 v[146:147], v[156:159], off
	v_pk_mul_f32 v[76:77], v[174:175], v[76:77] op_sel_hi:[0,1]
	v_pk_mul_f32 v[78:79], v[174:175], v[78:79] op_sel_hi:[0,1]
	v_pk_mul_f32 v[72:73], v[174:175], v[72:73] op_sel_hi:[0,1]
	v_pk_mul_f32 v[74:75], v[174:175], v[74:75] op_sel_hi:[0,1]
	v_pk_mul_f32 v[80:81], v[174:175], v[80:81] op_sel_hi:[0,1]
	v_pk_mul_f32 v[82:83], v[174:175], v[82:83] op_sel_hi:[0,1]
	v_pk_mul_f32 v[68:69], v[174:175], v[68:69] op_sel_hi:[0,1]
	v_pk_mul_f32 v[70:71], v[174:175], v[70:71] op_sel_hi:[0,1]
	v_pk_mul_f32 v[160:161], v[136:137], v[76:77] op_sel_hi:[0,1]
	v_pk_mul_f32 v[162:163], v[136:137], v[78:79] op_sel_hi:[0,1]
	v_pk_mul_f32 v[164:165], v[136:137], v[72:73] op_sel_hi:[0,1]
	v_pk_mul_f32 v[166:167], v[136:137], v[74:75] op_sel_hi:[0,1]
	v_exp_f32_e32 v160, v160
	v_exp_f32_e32 v161, v161
	v_exp_f32_e32 v162, v162
	v_exp_f32_e32 v163, v163
	v_exp_f32_e32 v164, v164
	v_exp_f32_e32 v165, v165
	v_exp_f32_e32 v166, v166
	v_exp_f32_e32 v167, v167
	v_pk_add_f32 v[160:161], v[138:139], v[160:161] op_sel_hi:[0,1]
	v_pk_add_f32 v[162:163], v[138:139], v[162:163] op_sel_hi:[0,1]
	v_pk_add_f32 v[164:165], v[138:139], v[164:165] op_sel_hi:[0,1]
	v_pk_add_f32 v[166:167], v[138:139], v[166:167] op_sel_hi:[0,1]
	v_rcp_f32_e32 v160, v160
	v_rcp_f32_e32 v161, v161
	v_rcp_f32_e32 v162, v162
	v_rcp_f32_e32 v163, v163
	v_rcp_f32_e32 v164, v164
	v_rcp_f32_e32 v165, v165
	v_rcp_f32_e32 v166, v166
	v_rcp_f32_e32 v167, v167
	v_pk_mul_f32 v[160:161], v[76:77], v[160:161]
	v_pk_mul_f32 v[162:163], v[78:79], v[162:163]
	v_pk_mul_f32 v[164:165], v[72:73], v[164:165]
	v_pk_mul_f32 v[166:167], v[74:75], v[166:167]
	v_pk_mul_f32 v[80:81], v[80:81], v[160:161]
	v_pk_mul_f32 v[82:83], v[82:83], v[162:163]
	v_pk_mul_f32 v[68:69], v[68:69], v[164:165]
	v_pk_mul_f32 v[70:71], v[70:71], v[166:167]
	v_cvt_pk_bf16_f32 v168, v80, v81
	v_cvt_pk_bf16_f32 v169, v82, v83
	v_cvt_pk_bf16_f32 v170, v68, v69
	v_cvt_pk_bf16_f32 v171, v70, v71
	global_store_dwordx4 v[180:181], v[168:171], off
	s_cmp_eq_u32 s20, 64
	s_cbranch_scc1 .LBB0_584
	v_fmamk_f32 v132, v229, 0x3a800000, v226
	v_add_u32_e32 v142, 0x80, v1
	v_mul_f32_e32 v133, 0x4b800000, v132
	v_cmp_gt_f32_e32 vcc, s48, v132
	v_mad_i64_i32 v[144:145], s[14:15], v142, s49, v[140:141]
	v_lshl_add_u64 v[146:147], v[144:145], 0, v[2:3]
	v_cndmask_b32_e32 v132, v132, v133, vcc
	v_rsq_f32_e32 v132, v132
	s_nop 0
	v_mul_f32_e32 v133, 0x45800000, v132
	v_cndmask_b32_e32 v134, v132, v133, vcc
	v_pk_mul_f32 v[60:61], v[134:135], v[60:61] op_sel_hi:[0,1]
	v_pk_mul_f32 v[62:63], v[134:135], v[62:63] op_sel_hi:[0,1]
	v_pk_mul_f32 v[52:53], v[134:135], v[52:53] op_sel_hi:[0,1]
	v_pk_mul_f32 v[54:55], v[134:135], v[54:55] op_sel_hi:[0,1]
	v_pk_mul_f32 v[64:65], v[134:135], v[64:65] op_sel_hi:[0,1]
	v_pk_mul_f32 v[66:67], v[134:135], v[66:67] op_sel_hi:[0,1]
	v_pk_mul_f32 v[56:57], v[134:135], v[56:57] op_sel_hi:[0,1]
	v_pk_mul_f32 v[58:59], v[134:135], v[58:59] op_sel_hi:[0,1]
	v_pk_mul_f32 v[148:149], v[136:137], v[60:61] op_sel_hi:[0,1]
	v_pk_mul_f32 v[150:151], v[136:137], v[62:63] op_sel_hi:[0,1]
	v_pk_mul_f32 v[152:153], v[136:137], v[52:53] op_sel_hi:[0,1]
	v_pk_mul_f32 v[154:155], v[136:137], v[54:55] op_sel_hi:[0,1]
	v_exp_f32_e32 v148, v148
	v_exp_f32_e32 v149, v149
	v_exp_f32_e32 v150, v150
	v_exp_f32_e32 v151, v151
	v_exp_f32_e32 v152, v152
	v_exp_f32_e32 v153, v153
	v_exp_f32_e32 v154, v154
	v_exp_f32_e32 v155, v155
	v_fmamk_f32 v172, v228, 0x3a800000, v226
	v_add_u32_e32 v176, 0x90, v1
	v_mul_f32_e32 v173, 0x4b800000, v172
	v_cmp_gt_f32_e32 vcc, s48, v172
	v_mad_i64_i32 v[178:179], s[14:15], v176, s49, v[140:141]
	v_lshl_add_u64 v[180:181], v[178:179], 0, v[2:3]
	v_cndmask_b32_e32 v172, v172, v173, vcc
	v_rsq_f32_e32 v172, v172
	s_nop 0
	v_mul_f32_e32 v173, 0x45800000, v172
	v_cndmask_b32_e32 v174, v172, v173, vcc
	v_pk_add_f32 v[148:149], v[138:139], v[148:149] op_sel_hi:[0,1]
	v_pk_add_f32 v[150:151], v[138:139], v[150:151] op_sel_hi:[0,1]
	v_pk_add_f32 v[152:153], v[138:139], v[152:153] op_sel_hi:[0,1]
	v_pk_add_f32 v[154:155], v[138:139], v[154:155] op_sel_hi:[0,1]
	v_rcp_f32_e32 v148, v148
	v_rcp_f32_e32 v149, v149
	v_rcp_f32_e32 v150, v150
	v_rcp_f32_e32 v151, v151
	v_rcp_f32_e32 v152, v152
	v_rcp_f32_e32 v153, v153
	v_rcp_f32_e32 v154, v154
	v_rcp_f32_e32 v155, v155
	v_pk_mul_f32 v[148:149], v[60:61], v[148:149]
	v_pk_mul_f32 v[150:151], v[62:63], v[150:151]
	v_pk_mul_f32 v[152:153], v[52:53], v[152:153]
	v_pk_mul_f32 v[154:155], v[54:55], v[154:155]
	v_pk_mul_f32 v[64:65], v[64:65], v[148:149]
	v_pk_mul_f32 v[66:67], v[66:67], v[150:151]
	v_pk_mul_f32 v[56:57], v[56:57], v[152:153]
	v_pk_mul_f32 v[58:59], v[58:59], v[154:155]
	v_cvt_pk_bf16_f32 v156, v64, v65
	v_cvt_pk_bf16_f32 v157, v66, v67
	v_cvt_pk_bf16_f32 v158, v56, v57
	v_cvt_pk_bf16_f32 v159, v58, v59
	global_store_dwordx4 v[146:147], v[156:159], off
	v_pk_mul_f32 v[44:45], v[174:175], v[44:45] op_sel_hi:[0,1]
	v_pk_mul_f32 v[46:47], v[174:175], v[46:47] op_sel_hi:[0,1]
	v_pk_mul_f32 v[36:37], v[174:175], v[36:37] op_sel_hi:[0,1]
	v_pk_mul_f32 v[38:39], v[174:175], v[38:39] op_sel_hi:[0,1]
	v_pk_mul_f32 v[48:49], v[174:175], v[48:49] op_sel_hi:[0,1]
	v_pk_mul_f32 v[50:51], v[174:175], v[50:51] op_sel_hi:[0,1]
	v_pk_mul_f32 v[40:41], v[174:175], v[40:41] op_sel_hi:[0,1]
	v_pk_mul_f32 v[42:43], v[174:175], v[42:43] op_sel_hi:[0,1]
	v_pk_mul_f32 v[160:161], v[136:137], v[44:45] op_sel_hi:[0,1]
	v_pk_mul_f32 v[162:163], v[136:137], v[46:47] op_sel_hi:[0,1]
	v_pk_mul_f32 v[164:165], v[136:137], v[36:37] op_sel_hi:[0,1]
	v_pk_mul_f32 v[166:167], v[136:137], v[38:39] op_sel_hi:[0,1]
	v_exp_f32_e32 v160, v160
	v_exp_f32_e32 v161, v161
	v_exp_f32_e32 v162, v162
	v_exp_f32_e32 v163, v163
	v_exp_f32_e32 v164, v164
	v_exp_f32_e32 v165, v165
	v_exp_f32_e32 v166, v166
	v_exp_f32_e32 v167, v167
	v_fmamk_f32 v132, v227, 0x3a800000, v226
	v_add_u32_e32 v142, 0xa0, v1
	v_mul_f32_e32 v133, 0x4b800000, v132
	v_cmp_gt_f32_e32 vcc, s48, v132
	v_mad_i64_i32 v[144:145], s[14:15], v142, s49, v[140:141]
	v_lshl_add_u64 v[146:147], v[144:145], 0, v[2:3]
	v_cndmask_b32_e32 v132, v132, v133, vcc
	v_rsq_f32_e32 v132, v132
	s_nop 0
	v_mul_f32_e32 v133, 0x45800000, v132
	v_cndmask_b32_e32 v134, v132, v133, vcc
	v_pk_add_f32 v[160:161], v[138:139], v[160:161] op_sel_hi:[0,1]
	v_pk_add_f32 v[162:163], v[138:139], v[162:163] op_sel_hi:[0,1]
	v_pk_add_f32 v[164:165], v[138:139], v[164:165] op_sel_hi:[0,1]
	v_pk_add_f32 v[166:167], v[138:139], v[166:167] op_sel_hi:[0,1]
	v_rcp_f32_e32 v160, v160
	v_rcp_f32_e32 v161, v161
	v_rcp_f32_e32 v162, v162
	v_rcp_f32_e32 v163, v163
	v_rcp_f32_e32 v164, v164
	v_rcp_f32_e32 v165, v165
	v_rcp_f32_e32 v166, v166
	v_rcp_f32_e32 v167, v167
	v_pk_mul_f32 v[160:161], v[44:45], v[160:161]
	v_pk_mul_f32 v[162:163], v[46:47], v[162:163]
	v_pk_mul_f32 v[164:165], v[36:37], v[164:165]
	v_pk_mul_f32 v[166:167], v[38:39], v[166:167]
	v_pk_mul_f32 v[48:49], v[48:49], v[160:161]
	v_pk_mul_f32 v[50:51], v[50:51], v[162:163]
	v_pk_mul_f32 v[40:41], v[40:41], v[164:165]
	v_pk_mul_f32 v[42:43], v[42:43], v[166:167]
	v_cvt_pk_bf16_f32 v168, v48, v49
	v_cvt_pk_bf16_f32 v169, v50, v51
	v_cvt_pk_bf16_f32 v170, v40, v41
	v_cvt_pk_bf16_f32 v171, v42, v43
	global_store_dwordx4 v[180:181], v[168:171], off
	v_pk_mul_f32 v[28:29], v[134:135], v[28:29] op_sel_hi:[0,1]
	v_pk_mul_f32 v[30:31], v[134:135], v[30:31] op_sel_hi:[0,1]
	v_pk_mul_f32 v[20:21], v[134:135], v[20:21] op_sel_hi:[0,1]
	v_pk_mul_f32 v[22:23], v[134:135], v[22:23] op_sel_hi:[0,1]
	v_pk_mul_f32 v[32:33], v[134:135], v[32:33] op_sel_hi:[0,1]
	v_pk_mul_f32 v[34:35], v[134:135], v[34:35] op_sel_hi:[0,1]
	v_pk_mul_f32 v[24:25], v[134:135], v[24:25] op_sel_hi:[0,1]
	v_pk_mul_f32 v[26:27], v[134:135], v[26:27] op_sel_hi:[0,1]
	v_pk_mul_f32 v[148:149], v[136:137], v[28:29] op_sel_hi:[0,1]
	v_pk_mul_f32 v[150:151], v[136:137], v[30:31] op_sel_hi:[0,1]
	v_pk_mul_f32 v[152:153], v[136:137], v[20:21] op_sel_hi:[0,1]
	v_pk_mul_f32 v[154:155], v[136:137], v[22:23] op_sel_hi:[0,1]
	v_exp_f32_e32 v148, v148
	v_exp_f32_e32 v149, v149
	v_exp_f32_e32 v150, v150
	v_exp_f32_e32 v151, v151
	v_exp_f32_e32 v152, v152
	v_exp_f32_e32 v153, v153
	v_exp_f32_e32 v154, v154
	v_exp_f32_e32 v155, v155
	v_fmamk_f32 v172, v218, 0x3a800000, v226
	v_add_u32_e32 v176, 0xb0, v1
	v_mul_f32_e32 v173, 0x4b800000, v172
	v_cmp_gt_f32_e32 vcc, s48, v172
	v_mad_i64_i32 v[178:179], s[14:15], v176, s49, v[140:141]
	v_lshl_add_u64 v[180:181], v[178:179], 0, v[2:3]
	v_cndmask_b32_e32 v172, v172, v173, vcc
	v_rsq_f32_e32 v172, v172
	s_nop 0
	v_mul_f32_e32 v173, 0x45800000, v172
	v_cndmask_b32_e32 v174, v172, v173, vcc
	v_pk_add_f32 v[148:149], v[138:139], v[148:149] op_sel_hi:[0,1]
	v_pk_add_f32 v[150:151], v[138:139], v[150:151] op_sel_hi:[0,1]
	v_pk_add_f32 v[152:153], v[138:139], v[152:153] op_sel_hi:[0,1]
	v_pk_add_f32 v[154:155], v[138:139], v[154:155] op_sel_hi:[0,1]
	v_rcp_f32_e32 v148, v148
	v_rcp_f32_e32 v149, v149
	v_rcp_f32_e32 v150, v150
	v_rcp_f32_e32 v151, v151
	v_rcp_f32_e32 v152, v152
	v_rcp_f32_e32 v153, v153
	v_rcp_f32_e32 v154, v154
	v_rcp_f32_e32 v155, v155
	v_pk_mul_f32 v[148:149], v[28:29], v[148:149]
	v_pk_mul_f32 v[150:151], v[30:31], v[150:151]
	v_pk_mul_f32 v[152:153], v[20:21], v[152:153]
	v_pk_mul_f32 v[154:155], v[22:23], v[154:155]
	v_pk_mul_f32 v[32:33], v[32:33], v[148:149]
	v_pk_mul_f32 v[34:35], v[34:35], v[150:151]
	v_pk_mul_f32 v[24:25], v[24:25], v[152:153]
	v_pk_mul_f32 v[26:27], v[26:27], v[154:155]
	v_cvt_pk_bf16_f32 v156, v32, v33
	v_cvt_pk_bf16_f32 v157, v34, v35
	v_cvt_pk_bf16_f32 v158, v24, v25
	v_cvt_pk_bf16_f32 v159, v26, v27
	global_store_dwordx4 v[146:147], v[156:159], off
	v_pk_mul_f32 v[12:13], v[174:175], v[12:13] op_sel_hi:[0,1]
	v_pk_mul_f32 v[14:15], v[174:175], v[14:15] op_sel_hi:[0,1]
	v_pk_mul_f32 v[4:5], v[174:175], v[4:5] op_sel_hi:[0,1]
	v_pk_mul_f32 v[6:7], v[174:175], v[6:7] op_sel_hi:[0,1]
	v_pk_mul_f32 v[16:17], v[174:175], v[16:17] op_sel_hi:[0,1]
	v_pk_mul_f32 v[18:19], v[174:175], v[18:19] op_sel_hi:[0,1]
	v_pk_mul_f32 v[8:9], v[174:175], v[8:9] op_sel_hi:[0,1]
	v_pk_mul_f32 v[10:11], v[174:175], v[10:11] op_sel_hi:[0,1]
	v_pk_mul_f32 v[160:161], v[136:137], v[12:13] op_sel_hi:[0,1]
	v_pk_mul_f32 v[162:163], v[136:137], v[14:15] op_sel_hi:[0,1]
	v_pk_mul_f32 v[164:165], v[136:137], v[4:5] op_sel_hi:[0,1]
	v_pk_mul_f32 v[166:167], v[136:137], v[6:7] op_sel_hi:[0,1]
	v_exp_f32_e32 v160, v160
	v_exp_f32_e32 v161, v161
	v_exp_f32_e32 v162, v162
	v_exp_f32_e32 v163, v163
	v_exp_f32_e32 v164, v164
	v_exp_f32_e32 v165, v165
	v_exp_f32_e32 v166, v166
	v_exp_f32_e32 v167, v167
	v_pk_add_f32 v[160:161], v[138:139], v[160:161] op_sel_hi:[0,1]
	v_pk_add_f32 v[162:163], v[138:139], v[162:163] op_sel_hi:[0,1]
	v_pk_add_f32 v[164:165], v[138:139], v[164:165] op_sel_hi:[0,1]
	v_pk_add_f32 v[166:167], v[138:139], v[166:167] op_sel_hi:[0,1]
	v_rcp_f32_e32 v160, v160
	v_rcp_f32_e32 v161, v161
	v_rcp_f32_e32 v162, v162
	v_rcp_f32_e32 v163, v163
	v_rcp_f32_e32 v164, v164
	v_rcp_f32_e32 v165, v165
	v_rcp_f32_e32 v166, v166
	v_rcp_f32_e32 v167, v167
	v_pk_mul_f32 v[160:161], v[12:13], v[160:161]
	v_pk_mul_f32 v[162:163], v[14:15], v[162:163]
	v_pk_mul_f32 v[164:165], v[4:5], v[164:165]
	v_pk_mul_f32 v[166:167], v[6:7], v[166:167]
	v_pk_mul_f32 v[16:17], v[16:17], v[160:161]
	v_pk_mul_f32 v[18:19], v[18:19], v[162:163]
	v_pk_mul_f32 v[8:9], v[8:9], v[164:165]
	v_pk_mul_f32 v[10:11], v[10:11], v[166:167]
	v_cvt_pk_bf16_f32 v168, v16, v17
	v_cvt_pk_bf16_f32 v169, v18, v19
	v_cvt_pk_bf16_f32 v170, v8, v9
	v_cvt_pk_bf16_f32 v171, v10, v11
	global_store_dwordx4 v[180:181], v[168:171], off

.LBB0_1355:
	s_waitcnt vmcnt(6)
	v_readlane_b32 s12, v255, 18
	v_readlane_b32 s13, v255, 19
	v_lshl_or_b32 v2, s22, 7, v221
	v_lshl_add_u32 v1, s20, 8, v219
	v_ashrrev_i32_e32 v3, 31, v2
	v_mov_b64_e32 v[140:141], s[12:13]
	v_mov_b32_e32 v136, 0xbfb8aa3b
	v_mov_b32_e32 v138, 1.0
	v_lshlrev_b64 v[2:3], 1, v[2:3]
	v_fmamk_f32 v132, v233, 0x3a800000, v226
	v_mul_f32_e32 v133, 0x4b800000, v132
	v_cmp_gt_f32_e32 vcc, s50, v132
	v_mad_i64_i32 v[144:145], s[12:13], v1, s51, v[140:141]
	v_lshl_add_u64 v[146:147], v[144:145], 0, v[2:3]
	v_cndmask_b32_e32 v132, v132, v133, vcc
	v_rsq_f32_e32 v132, v132
	s_nop 0
	v_mul_f32_e32 v133, 0x45800000, v132
	v_cndmask_b32_e32 v134, v132, v133, vcc
	v_pk_mul_f32 v[124:125], v[134:135], v[124:125] op_sel_hi:[0,1]
	v_pk_mul_f32 v[126:127], v[134:135], v[126:127] op_sel_hi:[0,1]
	v_pk_mul_f32 v[116:117], v[134:135], v[116:117] op_sel_hi:[0,1]
	v_pk_mul_f32 v[118:119], v[134:135], v[118:119] op_sel_hi:[0,1]
	v_pk_mul_f32 v[128:129], v[134:135], v[128:129] op_sel_hi:[0,1]
	v_pk_mul_f32 v[130:131], v[134:135], v[130:131] op_sel_hi:[0,1]
	v_pk_mul_f32 v[120:121], v[134:135], v[120:121] op_sel_hi:[0,1]
	v_pk_mul_f32 v[122:123], v[134:135], v[122:123] op_sel_hi:[0,1]
	v_pk_mul_f32 v[148:149], v[136:137], v[124:125] op_sel_hi:[0,1]
	v_pk_mul_f32 v[150:151], v[136:137], v[126:127] op_sel_hi:[0,1]
	v_pk_mul_f32 v[152:153], v[136:137], v[116:117] op_sel_hi:[0,1]
	v_pk_mul_f32 v[154:155], v[136:137], v[118:119] op_sel_hi:[0,1]
	v_exp_f32_e32 v148, v148
	v_exp_f32_e32 v149, v149
	v_exp_f32_e32 v150, v150
	v_exp_f32_e32 v151, v151
	v_exp_f32_e32 v152, v152
	v_exp_f32_e32 v153, v153
	v_exp_f32_e32 v154, v154
	v_exp_f32_e32 v155, v155
	v_fmamk_f32 v172, v232, 0x3a800000, v226
	v_or_b32_e32 v176, 16, v1
	v_mul_f32_e32 v173, 0x4b800000, v172
	v_cmp_gt_f32_e32 vcc, s50, v172
	v_mad_i64_i32 v[178:179], s[12:13], v176, s51, v[140:141]
	v_lshl_add_u64 v[180:181], v[178:179], 0, v[2:3]
	v_cndmask_b32_e32 v172, v172, v173, vcc
	v_rsq_f32_e32 v172, v172
	s_nop 0
	v_mul_f32_e32 v173, 0x45800000, v172
	v_cndmask_b32_e32 v174, v172, v173, vcc
	v_pk_add_f32 v[148:149], v[138:139], v[148:149] op_sel_hi:[0,1]
	v_pk_add_f32 v[150:151], v[138:139], v[150:151] op_sel_hi:[0,1]
	v_pk_add_f32 v[152:153], v[138:139], v[152:153] op_sel_hi:[0,1]
	v_pk_add_f32 v[154:155], v[138:139], v[154:155] op_sel_hi:[0,1]
	v_rcp_f32_e32 v148, v148
	v_rcp_f32_e32 v149, v149
	v_rcp_f32_e32 v150, v150
	v_rcp_f32_e32 v151, v151
	v_rcp_f32_e32 v152, v152
	v_rcp_f32_e32 v153, v153
	v_rcp_f32_e32 v154, v154
	v_rcp_f32_e32 v155, v155
	v_pk_mul_f32 v[148:149], v[124:125], v[148:149]
	v_pk_mul_f32 v[150:151], v[126:127], v[150:151]
	v_pk_mul_f32 v[152:153], v[116:117], v[152:153]
	v_pk_mul_f32 v[154:155], v[118:119], v[154:155]
	v_pk_mul_f32 v[128:129], v[128:129], v[148:149]
	v_pk_mul_f32 v[130:131], v[130:131], v[150:151]
	v_pk_mul_f32 v[120:121], v[120:121], v[152:153]
	v_pk_mul_f32 v[122:123], v[122:123], v[154:155]
	v_cvt_pk_bf16_f32 v156, v128, v129
	v_cvt_pk_bf16_f32 v157, v130, v131
	v_cvt_pk_bf16_f32 v158, v120, v121
	v_cvt_pk_bf16_f32 v159, v122, v123
	global_store_dwordx4 v[146:147], v[156:159], off
	v_pk_mul_f32 v[108:109], v[174:175], v[108:109] op_sel_hi:[0,1]
	v_pk_mul_f32 v[110:111], v[174:175], v[110:111] op_sel_hi:[0,1]
	v_pk_mul_f32 v[100:101], v[174:175], v[100:101] op_sel_hi:[0,1]
	v_pk_mul_f32 v[102:103], v[174:175], v[102:103] op_sel_hi:[0,1]
	v_pk_mul_f32 v[112:113], v[174:175], v[112:113] op_sel_hi:[0,1]
	v_pk_mul_f32 v[114:115], v[174:175], v[114:115] op_sel_hi:[0,1]
	v_pk_mul_f32 v[104:105], v[174:175], v[104:105] op_sel_hi:[0,1]
	v_pk_mul_f32 v[106:107], v[174:175], v[106:107] op_sel_hi:[0,1]
	v_pk_mul_f32 v[160:161], v[136:137], v[108:109] op_sel_hi:[0,1]
	v_pk_mul_f32 v[162:163], v[136:137], v[110:111] op_sel_hi:[0,1]
	v_pk_mul_f32 v[164:165], v[136:137], v[100:101] op_sel_hi:[0,1]
	v_pk_mul_f32 v[166:167], v[136:137], v[102:103] op_sel_hi:[0,1]
	v_exp_f32_e32 v160, v160
	v_exp_f32_e32 v161, v161
	v_exp_f32_e32 v162, v162
	v_exp_f32_e32 v163, v163
	v_exp_f32_e32 v164, v164
	v_exp_f32_e32 v165, v165
	v_exp_f32_e32 v166, v166
	v_exp_f32_e32 v167, v167
	v_fmamk_f32 v132, v231, 0x3a800000, v226
	v_or_b32_e32 v142, 32, v1
	v_mul_f32_e32 v133, 0x4b800000, v132
	v_cmp_gt_f32_e32 vcc, s50, v132
	v_mad_i64_i32 v[144:145], s[12:13], v142, s51, v[140:141]
	v_lshl_add_u64 v[146:147], v[144:145], 0, v[2:3]
	v_cndmask_b32_e32 v132, v132, v133, vcc
	v_rsq_f32_e32 v132, v132
	s_nop 0
	v_mul_f32_e32 v133, 0x45800000, v132
	v_cndmask_b32_e32 v134, v132, v133, vcc
	v_pk_add_f32 v[160:161], v[138:139], v[160:161] op_sel_hi:[0,1]
	v_pk_add_f32 v[162:163], v[138:139], v[162:163] op_sel_hi:[0,1]
	v_pk_add_f32 v[164:165], v[138:139], v[164:165] op_sel_hi:[0,1]
	v_pk_add_f32 v[166:167], v[138:139], v[166:167] op_sel_hi:[0,1]
	v_rcp_f32_e32 v160, v160
	v_rcp_f32_e32 v161, v161
	v_rcp_f32_e32 v162, v162
	v_rcp_f32_e32 v163, v163
	v_rcp_f32_e32 v164, v164
	v_rcp_f32_e32 v165, v165
	v_rcp_f32_e32 v166, v166
	v_rcp_f32_e32 v167, v167
	v_pk_mul_f32 v[160:161], v[108:109], v[160:161]
	v_pk_mul_f32 v[162:163], v[110:111], v[162:163]
	v_pk_mul_f32 v[164:165], v[100:101], v[164:165]
	v_pk_mul_f32 v[166:167], v[102:103], v[166:167]
	v_pk_mul_f32 v[112:113], v[112:113], v[160:161]
	v_pk_mul_f32 v[114:115], v[114:115], v[162:163]
	v_pk_mul_f32 v[104:105], v[104:105], v[164:165]
	v_pk_mul_f32 v[106:107], v[106:107], v[166:167]
	v_cvt_pk_bf16_f32 v168, v112, v113
	v_cvt_pk_bf16_f32 v169, v114, v115
	v_cvt_pk_bf16_f32 v170, v104, v105
	v_cvt_pk_bf16_f32 v171, v106, v107
	global_store_dwordx4 v[180:181], v[168:171], off
	v_pk_mul_f32 v[92:93], v[134:135], v[92:93] op_sel_hi:[0,1]
	v_pk_mul_f32 v[94:95], v[134:135], v[94:95] op_sel_hi:[0,1]
	v_pk_mul_f32 v[84:85], v[134:135], v[84:85] op_sel_hi:[0,1]
	v_pk_mul_f32 v[86:87], v[134:135], v[86:87] op_sel_hi:[0,1]
	v_pk_mul_f32 v[96:97], v[134:135], v[96:97] op_sel_hi:[0,1]
	v_pk_mul_f32 v[98:99], v[134:135], v[98:99] op_sel_hi:[0,1]
	v_pk_mul_f32 v[88:89], v[134:135], v[88:89] op_sel_hi:[0,1]
	v_pk_mul_f32 v[90:91], v[134:135], v[90:91] op_sel_hi:[0,1]
	v_pk_mul_f32 v[148:149], v[136:137], v[92:93] op_sel_hi:[0,1]
	v_pk_mul_f32 v[150:151], v[136:137], v[94:95] op_sel_hi:[0,1]
	v_pk_mul_f32 v[152:153], v[136:137], v[84:85] op_sel_hi:[0,1]
	v_pk_mul_f32 v[154:155], v[136:137], v[86:87] op_sel_hi:[0,1]
	v_exp_f32_e32 v148, v148
	v_exp_f32_e32 v149, v149
	v_exp_f32_e32 v150, v150
	v_exp_f32_e32 v151, v151
	v_exp_f32_e32 v152, v152
	v_exp_f32_e32 v153, v153
	v_exp_f32_e32 v154, v154
	v_exp_f32_e32 v155, v155
	v_fmamk_f32 v172, v230, 0x3a800000, v226
	v_or_b32_e32 v176, 48, v1
	v_mul_f32_e32 v173, 0x4b800000, v172
	v_cmp_gt_f32_e32 vcc, s50, v172
	v_mad_i64_i32 v[178:179], s[12:13], v176, s51, v[140:141]
	v_lshl_add_u64 v[180:181], v[178:179], 0, v[2:3]
	v_cndmask_b32_e32 v172, v172, v173, vcc
	v_rsq_f32_e32 v172, v172
	s_nop 0
	v_mul_f32_e32 v173, 0x45800000, v172
	v_cndmask_b32_e32 v174, v172, v173, vcc
	v_pk_add_f32 v[148:149], v[138:139], v[148:149] op_sel_hi:[0,1]
	v_pk_add_f32 v[150:151], v[138:139], v[150:151] op_sel_hi:[0,1]
	v_pk_add_f32 v[152:153], v[138:139], v[152:153] op_sel_hi:[0,1]
	v_pk_add_f32 v[154:155], v[138:139], v[154:155] op_sel_hi:[0,1]
	v_rcp_f32_e32 v148, v148
	v_rcp_f32_e32 v149, v149
	v_rcp_f32_e32 v150, v150
	v_rcp_f32_e32 v151, v151
	v_rcp_f32_e32 v152, v152
	v_rcp_f32_e32 v153, v153
	v_rcp_f32_e32 v154, v154
	v_rcp_f32_e32 v155, v155
	v_pk_mul_f32 v[148:149], v[92:93], v[148:149]
	v_pk_mul_f32 v[150:151], v[94:95], v[150:151]
	v_pk_mul_f32 v[152:153], v[84:85], v[152:153]
	v_pk_mul_f32 v[154:155], v[86:87], v[154:155]
	v_pk_mul_f32 v[96:97], v[96:97], v[148:149]
	v_pk_mul_f32 v[98:99], v[98:99], v[150:151]
	v_pk_mul_f32 v[88:89], v[88:89], v[152:153]
	v_pk_mul_f32 v[90:91], v[90:91], v[154:155]
	v_cvt_pk_bf16_f32 v156, v96, v97
	v_cvt_pk_bf16_f32 v157, v98, v99
	v_cvt_pk_bf16_f32 v158, v88, v89
	v_cvt_pk_bf16_f32 v159, v90, v91
	global_store_dwordx4 v[146:147], v[156:159], off
	v_pk_mul_f32 v[76:77], v[174:175], v[76:77] op_sel_hi:[0,1]
	v_pk_mul_f32 v[78:79], v[174:175], v[78:79] op_sel_hi:[0,1]
	v_pk_mul_f32 v[72:73], v[174:175], v[72:73] op_sel_hi:[0,1]
	v_pk_mul_f32 v[74:75], v[174:175], v[74:75] op_sel_hi:[0,1]
	v_pk_mul_f32 v[80:81], v[174:175], v[80:81] op_sel_hi:[0,1]
	v_pk_mul_f32 v[82:83], v[174:175], v[82:83] op_sel_hi:[0,1]
	v_pk_mul_f32 v[68:69], v[174:175], v[68:69] op_sel_hi:[0,1]
	v_pk_mul_f32 v[70:71], v[174:175], v[70:71] op_sel_hi:[0,1]
	v_pk_mul_f32 v[160:161], v[136:137], v[76:77] op_sel_hi:[0,1]
	v_pk_mul_f32 v[162:163], v[136:137], v[78:79] op_sel_hi:[0,1]
	v_pk_mul_f32 v[164:165], v[136:137], v[72:73] op_sel_hi:[0,1]
	v_pk_mul_f32 v[166:167], v[136:137], v[74:75] op_sel_hi:[0,1]
	v_exp_f32_e32 v160, v160
	v_exp_f32_e32 v161, v161
	v_exp_f32_e32 v162, v162
	v_exp_f32_e32 v163, v163
	v_exp_f32_e32 v164, v164
	v_exp_f32_e32 v165, v165
	v_exp_f32_e32 v166, v166
	v_exp_f32_e32 v167, v167
	v_pk_add_f32 v[160:161], v[138:139], v[160:161] op_sel_hi:[0,1]
	v_pk_add_f32 v[162:163], v[138:139], v[162:163] op_sel_hi:[0,1]
	v_pk_add_f32 v[164:165], v[138:139], v[164:165] op_sel_hi:[0,1]
	v_pk_add_f32 v[166:167], v[138:139], v[166:167] op_sel_hi:[0,1]
	v_rcp_f32_e32 v160, v160
	v_rcp_f32_e32 v161, v161
	v_rcp_f32_e32 v162, v162
	v_rcp_f32_e32 v163, v163
	v_rcp_f32_e32 v164, v164
	v_rcp_f32_e32 v165, v165
	v_rcp_f32_e32 v166, v166
	v_rcp_f32_e32 v167, v167
	v_pk_mul_f32 v[160:161], v[76:77], v[160:161]
	v_pk_mul_f32 v[162:163], v[78:79], v[162:163]
	v_pk_mul_f32 v[164:165], v[72:73], v[164:165]
	v_pk_mul_f32 v[166:167], v[74:75], v[166:167]
	v_pk_mul_f32 v[80:81], v[80:81], v[160:161]
	v_pk_mul_f32 v[82:83], v[82:83], v[162:163]
	v_pk_mul_f32 v[68:69], v[68:69], v[164:165]
	v_pk_mul_f32 v[70:71], v[70:71], v[166:167]
	v_cvt_pk_bf16_f32 v168, v80, v81
	v_cvt_pk_bf16_f32 v169, v82, v83
	v_cvt_pk_bf16_f32 v170, v68, v69
	v_cvt_pk_bf16_f32 v171, v70, v71
	global_store_dwordx4 v[180:181], v[168:171], off
	s_cmp_eq_u32 s20, 64
	s_cbranch_scc1 .LBB0_1357
	v_fmamk_f32 v132, v229, 0x3a800000, v226
	v_add_u32_e32 v142, 0x80, v1
	v_mul_f32_e32 v133, 0x4b800000, v132
	v_cmp_gt_f32_e32 vcc, s50, v132
	v_mad_i64_i32 v[144:145], s[12:13], v142, s51, v[140:141]
	v_lshl_add_u64 v[146:147], v[144:145], 0, v[2:3]
	v_cndmask_b32_e32 v132, v132, v133, vcc
	v_rsq_f32_e32 v132, v132
	s_nop 0
	v_mul_f32_e32 v133, 0x45800000, v132
	v_cndmask_b32_e32 v134, v132, v133, vcc
	v_pk_mul_f32 v[60:61], v[134:135], v[60:61] op_sel_hi:[0,1]
	v_pk_mul_f32 v[62:63], v[134:135], v[62:63] op_sel_hi:[0,1]
	v_pk_mul_f32 v[52:53], v[134:135], v[52:53] op_sel_hi:[0,1]
	v_pk_mul_f32 v[54:55], v[134:135], v[54:55] op_sel_hi:[0,1]
	v_pk_mul_f32 v[64:65], v[134:135], v[64:65] op_sel_hi:[0,1]
	v_pk_mul_f32 v[66:67], v[134:135], v[66:67] op_sel_hi:[0,1]
	v_pk_mul_f32 v[56:57], v[134:135], v[56:57] op_sel_hi:[0,1]
	v_pk_mul_f32 v[58:59], v[134:135], v[58:59] op_sel_hi:[0,1]
	v_pk_mul_f32 v[148:149], v[136:137], v[60:61] op_sel_hi:[0,1]
	v_pk_mul_f32 v[150:151], v[136:137], v[62:63] op_sel_hi:[0,1]
	v_pk_mul_f32 v[152:153], v[136:137], v[52:53] op_sel_hi:[0,1]
	v_pk_mul_f32 v[154:155], v[136:137], v[54:55] op_sel_hi:[0,1]
	v_exp_f32_e32 v148, v148
	v_exp_f32_e32 v149, v149
	v_exp_f32_e32 v150, v150
	v_exp_f32_e32 v151, v151
	v_exp_f32_e32 v152, v152
	v_exp_f32_e32 v153, v153
	v_exp_f32_e32 v154, v154
	v_exp_f32_e32 v155, v155
	v_fmamk_f32 v172, v228, 0x3a800000, v226
	v_add_u32_e32 v176, 0x90, v1
	v_mul_f32_e32 v173, 0x4b800000, v172
	v_cmp_gt_f32_e32 vcc, s50, v172
	v_mad_i64_i32 v[178:179], s[12:13], v176, s51, v[140:141]
	v_lshl_add_u64 v[180:181], v[178:179], 0, v[2:3]
	v_cndmask_b32_e32 v172, v172, v173, vcc
	v_rsq_f32_e32 v172, v172
	s_nop 0
	v_mul_f32_e32 v173, 0x45800000, v172
	v_cndmask_b32_e32 v174, v172, v173, vcc
	v_pk_add_f32 v[148:149], v[138:139], v[148:149] op_sel_hi:[0,1]
	v_pk_add_f32 v[150:151], v[138:139], v[150:151] op_sel_hi:[0,1]
	v_pk_add_f32 v[152:153], v[138:139], v[152:153] op_sel_hi:[0,1]
	v_pk_add_f32 v[154:155], v[138:139], v[154:155] op_sel_hi:[0,1]
	v_rcp_f32_e32 v148, v148
	v_rcp_f32_e32 v149, v149
	v_rcp_f32_e32 v150, v150
	v_rcp_f32_e32 v151, v151
	v_rcp_f32_e32 v152, v152
	v_rcp_f32_e32 v153, v153
	v_rcp_f32_e32 v154, v154
	v_rcp_f32_e32 v155, v155
	v_pk_mul_f32 v[148:149], v[60:61], v[148:149]
	v_pk_mul_f32 v[150:151], v[62:63], v[150:151]
	v_pk_mul_f32 v[152:153], v[52:53], v[152:153]
	v_pk_mul_f32 v[154:155], v[54:55], v[154:155]
	v_pk_mul_f32 v[64:65], v[64:65], v[148:149]
	v_pk_mul_f32 v[66:67], v[66:67], v[150:151]
	v_pk_mul_f32 v[56:57], v[56:57], v[152:153]
	v_pk_mul_f32 v[58:59], v[58:59], v[154:155]
	v_cvt_pk_bf16_f32 v156, v64, v65
	v_cvt_pk_bf16_f32 v157, v66, v67
	v_cvt_pk_bf16_f32 v158, v56, v57
	v_cvt_pk_bf16_f32 v159, v58, v59
	global_store_dwordx4 v[146:147], v[156:159], off
	v_pk_mul_f32 v[44:45], v[174:175], v[44:45] op_sel_hi:[0,1]
	v_pk_mul_f32 v[46:47], v[174:175], v[46:47] op_sel_hi:[0,1]
	v_pk_mul_f32 v[36:37], v[174:175], v[36:37] op_sel_hi:[0,1]
	v_pk_mul_f32 v[38:39], v[174:175], v[38:39] op_sel_hi:[0,1]
	v_pk_mul_f32 v[48:49], v[174:175], v[48:49] op_sel_hi:[0,1]
	v_pk_mul_f32 v[50:51], v[174:175], v[50:51] op_sel_hi:[0,1]
	v_pk_mul_f32 v[40:41], v[174:175], v[40:41] op_sel_hi:[0,1]
	v_pk_mul_f32 v[42:43], v[174:175], v[42:43] op_sel_hi:[0,1]
	v_pk_mul_f32 v[160:161], v[136:137], v[44:45] op_sel_hi:[0,1]
	v_pk_mul_f32 v[162:163], v[136:137], v[46:47] op_sel_hi:[0,1]
	v_pk_mul_f32 v[164:165], v[136:137], v[36:37] op_sel_hi:[0,1]
	v_pk_mul_f32 v[166:167], v[136:137], v[38:39] op_sel_hi:[0,1]
	v_exp_f32_e32 v160, v160
	v_exp_f32_e32 v161, v161
	v_exp_f32_e32 v162, v162
	v_exp_f32_e32 v163, v163
	v_exp_f32_e32 v164, v164
	v_exp_f32_e32 v165, v165
	v_exp_f32_e32 v166, v166
	v_exp_f32_e32 v167, v167
	v_fmamk_f32 v132, v227, 0x3a800000, v226
	v_add_u32_e32 v142, 0xa0, v1
	v_mul_f32_e32 v133, 0x4b800000, v132
	v_cmp_gt_f32_e32 vcc, s50, v132
	v_mad_i64_i32 v[144:145], s[12:13], v142, s51, v[140:141]
	v_lshl_add_u64 v[146:147], v[144:145], 0, v[2:3]
	v_cndmask_b32_e32 v132, v132, v133, vcc
	v_rsq_f32_e32 v132, v132
	s_nop 0
	v_mul_f32_e32 v133, 0x45800000, v132
	v_cndmask_b32_e32 v134, v132, v133, vcc
	v_pk_add_f32 v[160:161], v[138:139], v[160:161] op_sel_hi:[0,1]
	v_pk_add_f32 v[162:163], v[138:139], v[162:163] op_sel_hi:[0,1]
	v_pk_add_f32 v[164:165], v[138:139], v[164:165] op_sel_hi:[0,1]
	v_pk_add_f32 v[166:167], v[138:139], v[166:167] op_sel_hi:[0,1]
	v_rcp_f32_e32 v160, v160
	v_rcp_f32_e32 v161, v161
	v_rcp_f32_e32 v162, v162
	v_rcp_f32_e32 v163, v163
	v_rcp_f32_e32 v164, v164
	v_rcp_f32_e32 v165, v165
	v_rcp_f32_e32 v166, v166
	v_rcp_f32_e32 v167, v167
	v_pk_mul_f32 v[160:161], v[44:45], v[160:161]
	v_pk_mul_f32 v[162:163], v[46:47], v[162:163]
	v_pk_mul_f32 v[164:165], v[36:37], v[164:165]
	v_pk_mul_f32 v[166:167], v[38:39], v[166:167]
	v_pk_mul_f32 v[48:49], v[48:49], v[160:161]
	v_pk_mul_f32 v[50:51], v[50:51], v[162:163]
	v_pk_mul_f32 v[40:41], v[40:41], v[164:165]
	v_pk_mul_f32 v[42:43], v[42:43], v[166:167]
	v_cvt_pk_bf16_f32 v168, v48, v49
	v_cvt_pk_bf16_f32 v169, v50, v51
	v_cvt_pk_bf16_f32 v170, v40, v41
	v_cvt_pk_bf16_f32 v171, v42, v43
	global_store_dwordx4 v[180:181], v[168:171], off
	v_pk_mul_f32 v[28:29], v[134:135], v[28:29] op_sel_hi:[0,1]
	v_pk_mul_f32 v[30:31], v[134:135], v[30:31] op_sel_hi:[0,1]
	v_pk_mul_f32 v[20:21], v[134:135], v[20:21] op_sel_hi:[0,1]
	v_pk_mul_f32 v[22:23], v[134:135], v[22:23] op_sel_hi:[0,1]
	v_pk_mul_f32 v[32:33], v[134:135], v[32:33] op_sel_hi:[0,1]
	v_pk_mul_f32 v[34:35], v[134:135], v[34:35] op_sel_hi:[0,1]
	v_pk_mul_f32 v[24:25], v[134:135], v[24:25] op_sel_hi:[0,1]
	v_pk_mul_f32 v[26:27], v[134:135], v[26:27] op_sel_hi:[0,1]
	v_pk_mul_f32 v[148:149], v[136:137], v[28:29] op_sel_hi:[0,1]
	v_pk_mul_f32 v[150:151], v[136:137], v[30:31] op_sel_hi:[0,1]
	v_pk_mul_f32 v[152:153], v[136:137], v[20:21] op_sel_hi:[0,1]
	v_pk_mul_f32 v[154:155], v[136:137], v[22:23] op_sel_hi:[0,1]
	v_exp_f32_e32 v148, v148
	v_exp_f32_e32 v149, v149
	v_exp_f32_e32 v150, v150
	v_exp_f32_e32 v151, v151
	v_exp_f32_e32 v152, v152
	v_exp_f32_e32 v153, v153
	v_exp_f32_e32 v154, v154
	v_exp_f32_e32 v155, v155
	v_fmamk_f32 v172, v218, 0x3a800000, v226
	v_add_u32_e32 v176, 0xb0, v1
	v_mul_f32_e32 v173, 0x4b800000, v172
	v_cmp_gt_f32_e32 vcc, s50, v172
	v_mad_i64_i32 v[178:179], s[12:13], v176, s51, v[140:141]
	v_lshl_add_u64 v[180:181], v[178:179], 0, v[2:3]
	v_cndmask_b32_e32 v172, v172, v173, vcc
	v_rsq_f32_e32 v172, v172
	s_nop 0
	v_mul_f32_e32 v173, 0x45800000, v172
	v_cndmask_b32_e32 v174, v172, v173, vcc
	v_pk_add_f32 v[148:149], v[138:139], v[148:149] op_sel_hi:[0,1]
	v_pk_add_f32 v[150:151], v[138:139], v[150:151] op_sel_hi:[0,1]
	v_pk_add_f32 v[152:153], v[138:139], v[152:153] op_sel_hi:[0,1]
	v_pk_add_f32 v[154:155], v[138:139], v[154:155] op_sel_hi:[0,1]
	v_rcp_f32_e32 v148, v148
	v_rcp_f32_e32 v149, v149
	v_rcp_f32_e32 v150, v150
	v_rcp_f32_e32 v151, v151
	v_rcp_f32_e32 v152, v152
	v_rcp_f32_e32 v153, v153
	v_rcp_f32_e32 v154, v154
	v_rcp_f32_e32 v155, v155
	v_pk_mul_f32 v[148:149], v[28:29], v[148:149]
	v_pk_mul_f32 v[150:151], v[30:31], v[150:151]
	v_pk_mul_f32 v[152:153], v[20:21], v[152:153]
	v_pk_mul_f32 v[154:155], v[22:23], v[154:155]
	v_pk_mul_f32 v[32:33], v[32:33], v[148:149]
	v_pk_mul_f32 v[34:35], v[34:35], v[150:151]
	v_pk_mul_f32 v[24:25], v[24:25], v[152:153]
	v_pk_mul_f32 v[26:27], v[26:27], v[154:155]
	v_cvt_pk_bf16_f32 v156, v32, v33
	v_cvt_pk_bf16_f32 v157, v34, v35
	v_cvt_pk_bf16_f32 v158, v24, v25
	v_cvt_pk_bf16_f32 v159, v26, v27
	global_store_dwordx4 v[146:147], v[156:159], off
	v_pk_mul_f32 v[12:13], v[174:175], v[12:13] op_sel_hi:[0,1]
	v_pk_mul_f32 v[14:15], v[174:175], v[14:15] op_sel_hi:[0,1]
	v_pk_mul_f32 v[4:5], v[174:175], v[4:5] op_sel_hi:[0,1]
	v_pk_mul_f32 v[6:7], v[174:175], v[6:7] op_sel_hi:[0,1]
	v_pk_mul_f32 v[16:17], v[174:175], v[16:17] op_sel_hi:[0,1]
	v_pk_mul_f32 v[18:19], v[174:175], v[18:19] op_sel_hi:[0,1]
	v_pk_mul_f32 v[8:9], v[174:175], v[8:9] op_sel_hi:[0,1]
	v_pk_mul_f32 v[10:11], v[174:175], v[10:11] op_sel_hi:[0,1]
	v_pk_mul_f32 v[160:161], v[136:137], v[12:13] op_sel_hi:[0,1]
	v_pk_mul_f32 v[162:163], v[136:137], v[14:15] op_sel_hi:[0,1]
	v_pk_mul_f32 v[164:165], v[136:137], v[4:5] op_sel_hi:[0,1]
	v_pk_mul_f32 v[166:167], v[136:137], v[6:7] op_sel_hi:[0,1]
	v_exp_f32_e32 v160, v160
	v_exp_f32_e32 v161, v161
	v_exp_f32_e32 v162, v162
	v_exp_f32_e32 v163, v163
	v_exp_f32_e32 v164, v164
	v_exp_f32_e32 v165, v165
	v_exp_f32_e32 v166, v166
	v_exp_f32_e32 v167, v167
	v_pk_add_f32 v[160:161], v[138:139], v[160:161] op_sel_hi:[0,1]
	v_pk_add_f32 v[162:163], v[138:139], v[162:163] op_sel_hi:[0,1]
	v_pk_add_f32 v[164:165], v[138:139], v[164:165] op_sel_hi:[0,1]
	v_pk_add_f32 v[166:167], v[138:139], v[166:167] op_sel_hi:[0,1]
	v_rcp_f32_e32 v160, v160
	v_rcp_f32_e32 v161, v161
	v_rcp_f32_e32 v162, v162
	v_rcp_f32_e32 v163, v163
	v_rcp_f32_e32 v164, v164
	v_rcp_f32_e32 v165, v165
	v_rcp_f32_e32 v166, v166
	v_rcp_f32_e32 v167, v167
	v_pk_mul_f32 v[160:161], v[12:13], v[160:161]
	v_pk_mul_f32 v[162:163], v[14:15], v[162:163]
	v_pk_mul_f32 v[164:165], v[4:5], v[164:165]
	v_pk_mul_f32 v[166:167], v[6:7], v[166:167]
	v_pk_mul_f32 v[16:17], v[16:17], v[160:161]
	v_pk_mul_f32 v[18:19], v[18:19], v[162:163]
	v_pk_mul_f32 v[8:9], v[8:9], v[164:165]
	v_pk_mul_f32 v[10:11], v[10:11], v[166:167]
	v_cvt_pk_bf16_f32 v168, v16, v17
	v_cvt_pk_bf16_f32 v169, v18, v19
	v_cvt_pk_bf16_f32 v170, v8, v9
	v_cvt_pk_bf16_f32 v171, v10, v11
	global_store_dwordx4 v[180:181], v[168:171], off

.LBB0_2901:
	s_waitcnt vmcnt(6)
	v_readlane_b32 s12, v255, 18
	v_readlane_b32 s13, v255, 19
	v_lshl_or_b32 v2, s24, 7, v221
	v_lshl_add_u32 v1, s22, 8, v219
	v_ashrrev_i32_e32 v3, 31, v2
	v_mov_b64_e32 v[140:141], s[12:13]
	v_mov_b32_e32 v136, 0xbfb8aa3b
	v_mov_b32_e32 v138, 1.0
	v_lshlrev_b64 v[2:3], 1, v[2:3]
	v_fmamk_f32 v132, v233, 0x3a800000, v226
	v_mul_f32_e32 v133, 0x4b800000, v132
	v_cmp_gt_f32_e32 vcc, s47, v132
	v_mad_i64_i32 v[144:145], s[12:13], v1, s55, v[140:141]
	v_lshl_add_u64 v[146:147], v[144:145], 0, v[2:3]
	v_cndmask_b32_e32 v132, v132, v133, vcc
	v_rsq_f32_e32 v132, v132
	s_nop 0
	v_mul_f32_e32 v133, 0x45800000, v132
	v_cndmask_b32_e32 v134, v132, v133, vcc
	v_pk_mul_f32 v[124:125], v[134:135], v[124:125] op_sel_hi:[0,1]
	v_pk_mul_f32 v[126:127], v[134:135], v[126:127] op_sel_hi:[0,1]
	v_pk_mul_f32 v[116:117], v[134:135], v[116:117] op_sel_hi:[0,1]
	v_pk_mul_f32 v[118:119], v[134:135], v[118:119] op_sel_hi:[0,1]
	v_pk_mul_f32 v[128:129], v[134:135], v[128:129] op_sel_hi:[0,1]
	v_pk_mul_f32 v[130:131], v[134:135], v[130:131] op_sel_hi:[0,1]
	v_pk_mul_f32 v[120:121], v[134:135], v[120:121] op_sel_hi:[0,1]
	v_pk_mul_f32 v[122:123], v[134:135], v[122:123] op_sel_hi:[0,1]
	v_pk_mul_f32 v[148:149], v[136:137], v[124:125] op_sel_hi:[0,1]
	v_pk_mul_f32 v[150:151], v[136:137], v[126:127] op_sel_hi:[0,1]
	v_pk_mul_f32 v[152:153], v[136:137], v[116:117] op_sel_hi:[0,1]
	v_pk_mul_f32 v[154:155], v[136:137], v[118:119] op_sel_hi:[0,1]
	v_exp_f32_e32 v148, v148
	v_exp_f32_e32 v149, v149
	v_exp_f32_e32 v150, v150
	v_exp_f32_e32 v151, v151
	v_exp_f32_e32 v152, v152
	v_exp_f32_e32 v153, v153
	v_exp_f32_e32 v154, v154
	v_exp_f32_e32 v155, v155
	v_fmamk_f32 v172, v232, 0x3a800000, v226
	v_or_b32_e32 v176, 16, v1
	v_mul_f32_e32 v173, 0x4b800000, v172
	v_cmp_gt_f32_e32 vcc, s47, v172
	v_mad_i64_i32 v[178:179], s[12:13], v176, s55, v[140:141]
	v_lshl_add_u64 v[180:181], v[178:179], 0, v[2:3]
	v_cndmask_b32_e32 v172, v172, v173, vcc
	v_rsq_f32_e32 v172, v172
	s_nop 0
	v_mul_f32_e32 v173, 0x45800000, v172
	v_cndmask_b32_e32 v174, v172, v173, vcc
	v_pk_add_f32 v[148:149], v[138:139], v[148:149] op_sel_hi:[0,1]
	v_pk_add_f32 v[150:151], v[138:139], v[150:151] op_sel_hi:[0,1]
	v_pk_add_f32 v[152:153], v[138:139], v[152:153] op_sel_hi:[0,1]
	v_pk_add_f32 v[154:155], v[138:139], v[154:155] op_sel_hi:[0,1]
	v_rcp_f32_e32 v148, v148
	v_rcp_f32_e32 v149, v149
	v_rcp_f32_e32 v150, v150
	v_rcp_f32_e32 v151, v151
	v_rcp_f32_e32 v152, v152
	v_rcp_f32_e32 v153, v153
	v_rcp_f32_e32 v154, v154
	v_rcp_f32_e32 v155, v155
	v_pk_mul_f32 v[148:149], v[124:125], v[148:149]
	v_pk_mul_f32 v[150:151], v[126:127], v[150:151]
	v_pk_mul_f32 v[152:153], v[116:117], v[152:153]
	v_pk_mul_f32 v[154:155], v[118:119], v[154:155]
	v_pk_mul_f32 v[128:129], v[128:129], v[148:149]
	v_pk_mul_f32 v[130:131], v[130:131], v[150:151]
	v_pk_mul_f32 v[120:121], v[120:121], v[152:153]
	v_pk_mul_f32 v[122:123], v[122:123], v[154:155]
	v_cvt_pk_bf16_f32 v156, v128, v129
	v_cvt_pk_bf16_f32 v157, v130, v131
	v_cvt_pk_bf16_f32 v158, v120, v121
	v_cvt_pk_bf16_f32 v159, v122, v123
	global_store_dwordx4 v[146:147], v[156:159], off
	v_pk_mul_f32 v[108:109], v[174:175], v[108:109] op_sel_hi:[0,1]
	v_pk_mul_f32 v[110:111], v[174:175], v[110:111] op_sel_hi:[0,1]
	v_pk_mul_f32 v[100:101], v[174:175], v[100:101] op_sel_hi:[0,1]
	v_pk_mul_f32 v[102:103], v[174:175], v[102:103] op_sel_hi:[0,1]
	v_pk_mul_f32 v[112:113], v[174:175], v[112:113] op_sel_hi:[0,1]
	v_pk_mul_f32 v[114:115], v[174:175], v[114:115] op_sel_hi:[0,1]
	v_pk_mul_f32 v[104:105], v[174:175], v[104:105] op_sel_hi:[0,1]
	v_pk_mul_f32 v[106:107], v[174:175], v[106:107] op_sel_hi:[0,1]
	v_pk_mul_f32 v[160:161], v[136:137], v[108:109] op_sel_hi:[0,1]
	v_pk_mul_f32 v[162:163], v[136:137], v[110:111] op_sel_hi:[0,1]
	v_pk_mul_f32 v[164:165], v[136:137], v[100:101] op_sel_hi:[0,1]
	v_pk_mul_f32 v[166:167], v[136:137], v[102:103] op_sel_hi:[0,1]
	v_exp_f32_e32 v160, v160
	v_exp_f32_e32 v161, v161
	v_exp_f32_e32 v162, v162
	v_exp_f32_e32 v163, v163
	v_exp_f32_e32 v164, v164
	v_exp_f32_e32 v165, v165
	v_exp_f32_e32 v166, v166
	v_exp_f32_e32 v167, v167
	v_fmamk_f32 v132, v231, 0x3a800000, v226
	v_or_b32_e32 v142, 32, v1
	v_mul_f32_e32 v133, 0x4b800000, v132
	v_cmp_gt_f32_e32 vcc, s47, v132
	v_mad_i64_i32 v[144:145], s[12:13], v142, s55, v[140:141]
	v_lshl_add_u64 v[146:147], v[144:145], 0, v[2:3]
	v_cndmask_b32_e32 v132, v132, v133, vcc
	v_rsq_f32_e32 v132, v132
	s_nop 0
	v_mul_f32_e32 v133, 0x45800000, v132
	v_cndmask_b32_e32 v134, v132, v133, vcc
	v_pk_add_f32 v[160:161], v[138:139], v[160:161] op_sel_hi:[0,1]
	v_pk_add_f32 v[162:163], v[138:139], v[162:163] op_sel_hi:[0,1]
	v_pk_add_f32 v[164:165], v[138:139], v[164:165] op_sel_hi:[0,1]
	v_pk_add_f32 v[166:167], v[138:139], v[166:167] op_sel_hi:[0,1]
	v_rcp_f32_e32 v160, v160
	v_rcp_f32_e32 v161, v161
	v_rcp_f32_e32 v162, v162
	v_rcp_f32_e32 v163, v163
	v_rcp_f32_e32 v164, v164
	v_rcp_f32_e32 v165, v165
	v_rcp_f32_e32 v166, v166
	v_rcp_f32_e32 v167, v167
	v_pk_mul_f32 v[160:161], v[108:109], v[160:161]
	v_pk_mul_f32 v[162:163], v[110:111], v[162:163]
	v_pk_mul_f32 v[164:165], v[100:101], v[164:165]
	v_pk_mul_f32 v[166:167], v[102:103], v[166:167]
	v_pk_mul_f32 v[112:113], v[112:113], v[160:161]
	v_pk_mul_f32 v[114:115], v[114:115], v[162:163]
	v_pk_mul_f32 v[104:105], v[104:105], v[164:165]
	v_pk_mul_f32 v[106:107], v[106:107], v[166:167]
	v_cvt_pk_bf16_f32 v168, v112, v113
	v_cvt_pk_bf16_f32 v169, v114, v115
	v_cvt_pk_bf16_f32 v170, v104, v105
	v_cvt_pk_bf16_f32 v171, v106, v107
	global_store_dwordx4 v[180:181], v[168:171], off
	v_pk_mul_f32 v[92:93], v[134:135], v[92:93] op_sel_hi:[0,1]
	v_pk_mul_f32 v[94:95], v[134:135], v[94:95] op_sel_hi:[0,1]
	v_pk_mul_f32 v[84:85], v[134:135], v[84:85] op_sel_hi:[0,1]
	v_pk_mul_f32 v[86:87], v[134:135], v[86:87] op_sel_hi:[0,1]
	v_pk_mul_f32 v[96:97], v[134:135], v[96:97] op_sel_hi:[0,1]
	v_pk_mul_f32 v[98:99], v[134:135], v[98:99] op_sel_hi:[0,1]
	v_pk_mul_f32 v[88:89], v[134:135], v[88:89] op_sel_hi:[0,1]
	v_pk_mul_f32 v[90:91], v[134:135], v[90:91] op_sel_hi:[0,1]
	v_pk_mul_f32 v[148:149], v[136:137], v[92:93] op_sel_hi:[0,1]
	v_pk_mul_f32 v[150:151], v[136:137], v[94:95] op_sel_hi:[0,1]
	v_pk_mul_f32 v[152:153], v[136:137], v[84:85] op_sel_hi:[0,1]
	v_pk_mul_f32 v[154:155], v[136:137], v[86:87] op_sel_hi:[0,1]
	v_exp_f32_e32 v148, v148
	v_exp_f32_e32 v149, v149
	v_exp_f32_e32 v150, v150
	v_exp_f32_e32 v151, v151
	v_exp_f32_e32 v152, v152
	v_exp_f32_e32 v153, v153
	v_exp_f32_e32 v154, v154
	v_exp_f32_e32 v155, v155
	v_fmamk_f32 v172, v230, 0x3a800000, v226
	v_or_b32_e32 v176, 48, v1
	v_mul_f32_e32 v173, 0x4b800000, v172
	v_cmp_gt_f32_e32 vcc, s47, v172
	v_mad_i64_i32 v[178:179], s[12:13], v176, s55, v[140:141]
	v_lshl_add_u64 v[180:181], v[178:179], 0, v[2:3]
	v_cndmask_b32_e32 v172, v172, v173, vcc
	v_rsq_f32_e32 v172, v172
	s_nop 0
	v_mul_f32_e32 v173, 0x45800000, v172
	v_cndmask_b32_e32 v174, v172, v173, vcc
	v_pk_add_f32 v[148:149], v[138:139], v[148:149] op_sel_hi:[0,1]
	v_pk_add_f32 v[150:151], v[138:139], v[150:151] op_sel_hi:[0,1]
	v_pk_add_f32 v[152:153], v[138:139], v[152:153] op_sel_hi:[0,1]
	v_pk_add_f32 v[154:155], v[138:139], v[154:155] op_sel_hi:[0,1]
	v_rcp_f32_e32 v148, v148
	v_rcp_f32_e32 v149, v149
	v_rcp_f32_e32 v150, v150
	v_rcp_f32_e32 v151, v151
	v_rcp_f32_e32 v152, v152
	v_rcp_f32_e32 v153, v153
	v_rcp_f32_e32 v154, v154
	v_rcp_f32_e32 v155, v155
	v_pk_mul_f32 v[148:149], v[92:93], v[148:149]
	v_pk_mul_f32 v[150:151], v[94:95], v[150:151]
	v_pk_mul_f32 v[152:153], v[84:85], v[152:153]
	v_pk_mul_f32 v[154:155], v[86:87], v[154:155]
	v_pk_mul_f32 v[96:97], v[96:97], v[148:149]
	v_pk_mul_f32 v[98:99], v[98:99], v[150:151]
	v_pk_mul_f32 v[88:89], v[88:89], v[152:153]
	v_pk_mul_f32 v[90:91], v[90:91], v[154:155]
	v_cvt_pk_bf16_f32 v156, v96, v97
	v_cvt_pk_bf16_f32 v157, v98, v99
	v_cvt_pk_bf16_f32 v158, v88, v89
	v_cvt_pk_bf16_f32 v159, v90, v91
	global_store_dwordx4 v[146:147], v[156:159], off
	v_pk_mul_f32 v[76:77], v[174:175], v[76:77] op_sel_hi:[0,1]
	v_pk_mul_f32 v[78:79], v[174:175], v[78:79] op_sel_hi:[0,1]
	v_pk_mul_f32 v[72:73], v[174:175], v[72:73] op_sel_hi:[0,1]
	v_pk_mul_f32 v[74:75], v[174:175], v[74:75] op_sel_hi:[0,1]
	v_pk_mul_f32 v[80:81], v[174:175], v[80:81] op_sel_hi:[0,1]
	v_pk_mul_f32 v[82:83], v[174:175], v[82:83] op_sel_hi:[0,1]
	v_pk_mul_f32 v[68:69], v[174:175], v[68:69] op_sel_hi:[0,1]
	v_pk_mul_f32 v[70:71], v[174:175], v[70:71] op_sel_hi:[0,1]
	v_pk_mul_f32 v[160:161], v[136:137], v[76:77] op_sel_hi:[0,1]
	v_pk_mul_f32 v[162:163], v[136:137], v[78:79] op_sel_hi:[0,1]
	v_pk_mul_f32 v[164:165], v[136:137], v[72:73] op_sel_hi:[0,1]
	v_pk_mul_f32 v[166:167], v[136:137], v[74:75] op_sel_hi:[0,1]
	v_exp_f32_e32 v160, v160
	v_exp_f32_e32 v161, v161
	v_exp_f32_e32 v162, v162
	v_exp_f32_e32 v163, v163
	v_exp_f32_e32 v164, v164
	v_exp_f32_e32 v165, v165
	v_exp_f32_e32 v166, v166
	v_exp_f32_e32 v167, v167
	v_pk_add_f32 v[160:161], v[138:139], v[160:161] op_sel_hi:[0,1]
	v_pk_add_f32 v[162:163], v[138:139], v[162:163] op_sel_hi:[0,1]
	v_pk_add_f32 v[164:165], v[138:139], v[164:165] op_sel_hi:[0,1]
	v_pk_add_f32 v[166:167], v[138:139], v[166:167] op_sel_hi:[0,1]
	v_rcp_f32_e32 v160, v160
	v_rcp_f32_e32 v161, v161
	v_rcp_f32_e32 v162, v162
	v_rcp_f32_e32 v163, v163
	v_rcp_f32_e32 v164, v164
	v_rcp_f32_e32 v165, v165
	v_rcp_f32_e32 v166, v166
	v_rcp_f32_e32 v167, v167
	v_pk_mul_f32 v[160:161], v[76:77], v[160:161]
	v_pk_mul_f32 v[162:163], v[78:79], v[162:163]
	v_pk_mul_f32 v[164:165], v[72:73], v[164:165]
	v_pk_mul_f32 v[166:167], v[74:75], v[166:167]
	v_pk_mul_f32 v[80:81], v[80:81], v[160:161]
	v_pk_mul_f32 v[82:83], v[82:83], v[162:163]
	v_pk_mul_f32 v[68:69], v[68:69], v[164:165]
	v_pk_mul_f32 v[70:71], v[70:71], v[166:167]
	v_cvt_pk_bf16_f32 v168, v80, v81
	v_cvt_pk_bf16_f32 v169, v82, v83
	v_cvt_pk_bf16_f32 v170, v68, v69
	v_cvt_pk_bf16_f32 v171, v70, v71
	global_store_dwordx4 v[180:181], v[168:171], off
	s_cmp_eq_u32 s22, 64
	s_cbranch_scc1 .LBB0_2903
	v_fmamk_f32 v132, v229, 0x3a800000, v226
	v_add_u32_e32 v142, 0x80, v1
	v_mul_f32_e32 v133, 0x4b800000, v132
	v_cmp_gt_f32_e32 vcc, s47, v132
	v_mad_i64_i32 v[144:145], s[12:13], v142, s55, v[140:141]
	v_lshl_add_u64 v[146:147], v[144:145], 0, v[2:3]
	v_cndmask_b32_e32 v132, v132, v133, vcc
	v_rsq_f32_e32 v132, v132
	s_nop 0
	v_mul_f32_e32 v133, 0x45800000, v132
	v_cndmask_b32_e32 v134, v132, v133, vcc
	v_pk_mul_f32 v[60:61], v[134:135], v[60:61] op_sel_hi:[0,1]
	v_pk_mul_f32 v[62:63], v[134:135], v[62:63] op_sel_hi:[0,1]
	v_pk_mul_f32 v[52:53], v[134:135], v[52:53] op_sel_hi:[0,1]
	v_pk_mul_f32 v[54:55], v[134:135], v[54:55] op_sel_hi:[0,1]
	v_pk_mul_f32 v[64:65], v[134:135], v[64:65] op_sel_hi:[0,1]
	v_pk_mul_f32 v[66:67], v[134:135], v[66:67] op_sel_hi:[0,1]
	v_pk_mul_f32 v[56:57], v[134:135], v[56:57] op_sel_hi:[0,1]
	v_pk_mul_f32 v[58:59], v[134:135], v[58:59] op_sel_hi:[0,1]
	v_pk_mul_f32 v[148:149], v[136:137], v[60:61] op_sel_hi:[0,1]
	v_pk_mul_f32 v[150:151], v[136:137], v[62:63] op_sel_hi:[0,1]
	v_pk_mul_f32 v[152:153], v[136:137], v[52:53] op_sel_hi:[0,1]
	v_pk_mul_f32 v[154:155], v[136:137], v[54:55] op_sel_hi:[0,1]
	v_exp_f32_e32 v148, v148
	v_exp_f32_e32 v149, v149
	v_exp_f32_e32 v150, v150
	v_exp_f32_e32 v151, v151
	v_exp_f32_e32 v152, v152
	v_exp_f32_e32 v153, v153
	v_exp_f32_e32 v154, v154
	v_exp_f32_e32 v155, v155
	v_fmamk_f32 v172, v228, 0x3a800000, v226
	v_add_u32_e32 v176, 0x90, v1
	v_mul_f32_e32 v173, 0x4b800000, v172
	v_cmp_gt_f32_e32 vcc, s47, v172
	v_mad_i64_i32 v[178:179], s[12:13], v176, s55, v[140:141]
	v_lshl_add_u64 v[180:181], v[178:179], 0, v[2:3]
	v_cndmask_b32_e32 v172, v172, v173, vcc
	v_rsq_f32_e32 v172, v172
	s_nop 0
	v_mul_f32_e32 v173, 0x45800000, v172
	v_cndmask_b32_e32 v174, v172, v173, vcc
	v_pk_add_f32 v[148:149], v[138:139], v[148:149] op_sel_hi:[0,1]
	v_pk_add_f32 v[150:151], v[138:139], v[150:151] op_sel_hi:[0,1]
	v_pk_add_f32 v[152:153], v[138:139], v[152:153] op_sel_hi:[0,1]
	v_pk_add_f32 v[154:155], v[138:139], v[154:155] op_sel_hi:[0,1]
	v_rcp_f32_e32 v148, v148
	v_rcp_f32_e32 v149, v149
	v_rcp_f32_e32 v150, v150
	v_rcp_f32_e32 v151, v151
	v_rcp_f32_e32 v152, v152
	v_rcp_f32_e32 v153, v153
	v_rcp_f32_e32 v154, v154
	v_rcp_f32_e32 v155, v155
	v_pk_mul_f32 v[148:149], v[60:61], v[148:149]
	v_pk_mul_f32 v[150:151], v[62:63], v[150:151]
	v_pk_mul_f32 v[152:153], v[52:53], v[152:153]
	v_pk_mul_f32 v[154:155], v[54:55], v[154:155]
	v_pk_mul_f32 v[64:65], v[64:65], v[148:149]
	v_pk_mul_f32 v[66:67], v[66:67], v[150:151]
	v_pk_mul_f32 v[56:57], v[56:57], v[152:153]
	v_pk_mul_f32 v[58:59], v[58:59], v[154:155]
	v_cvt_pk_bf16_f32 v156, v64, v65
	v_cvt_pk_bf16_f32 v157, v66, v67
	v_cvt_pk_bf16_f32 v158, v56, v57
	v_cvt_pk_bf16_f32 v159, v58, v59
	global_store_dwordx4 v[146:147], v[156:159], off
	v_pk_mul_f32 v[44:45], v[174:175], v[44:45] op_sel_hi:[0,1]
	v_pk_mul_f32 v[46:47], v[174:175], v[46:47] op_sel_hi:[0,1]
	v_pk_mul_f32 v[36:37], v[174:175], v[36:37] op_sel_hi:[0,1]
	v_pk_mul_f32 v[38:39], v[174:175], v[38:39] op_sel_hi:[0,1]
	v_pk_mul_f32 v[48:49], v[174:175], v[48:49] op_sel_hi:[0,1]
	v_pk_mul_f32 v[50:51], v[174:175], v[50:51] op_sel_hi:[0,1]
	v_pk_mul_f32 v[40:41], v[174:175], v[40:41] op_sel_hi:[0,1]
	v_pk_mul_f32 v[42:43], v[174:175], v[42:43] op_sel_hi:[0,1]
	v_pk_mul_f32 v[160:161], v[136:137], v[44:45] op_sel_hi:[0,1]
	v_pk_mul_f32 v[162:163], v[136:137], v[46:47] op_sel_hi:[0,1]
	v_pk_mul_f32 v[164:165], v[136:137], v[36:37] op_sel_hi:[0,1]
	v_pk_mul_f32 v[166:167], v[136:137], v[38:39] op_sel_hi:[0,1]
	v_exp_f32_e32 v160, v160
	v_exp_f32_e32 v161, v161
	v_exp_f32_e32 v162, v162
	v_exp_f32_e32 v163, v163
	v_exp_f32_e32 v164, v164
	v_exp_f32_e32 v165, v165
	v_exp_f32_e32 v166, v166
	v_exp_f32_e32 v167, v167
	v_fmamk_f32 v132, v227, 0x3a800000, v226
	v_add_u32_e32 v142, 0xa0, v1
	v_mul_f32_e32 v133, 0x4b800000, v132
	v_cmp_gt_f32_e32 vcc, s47, v132
	v_mad_i64_i32 v[144:145], s[12:13], v142, s55, v[140:141]
	v_lshl_add_u64 v[146:147], v[144:145], 0, v[2:3]
	v_cndmask_b32_e32 v132, v132, v133, vcc
	v_rsq_f32_e32 v132, v132
	s_nop 0
	v_mul_f32_e32 v133, 0x45800000, v132
	v_cndmask_b32_e32 v134, v132, v133, vcc
	v_pk_add_f32 v[160:161], v[138:139], v[160:161] op_sel_hi:[0,1]
	v_pk_add_f32 v[162:163], v[138:139], v[162:163] op_sel_hi:[0,1]
	v_pk_add_f32 v[164:165], v[138:139], v[164:165] op_sel_hi:[0,1]
	v_pk_add_f32 v[166:167], v[138:139], v[166:167] op_sel_hi:[0,1]
	v_rcp_f32_e32 v160, v160
	v_rcp_f32_e32 v161, v161
	v_rcp_f32_e32 v162, v162
	v_rcp_f32_e32 v163, v163
	v_rcp_f32_e32 v164, v164
	v_rcp_f32_e32 v165, v165
	v_rcp_f32_e32 v166, v166
	v_rcp_f32_e32 v167, v167
	v_pk_mul_f32 v[160:161], v[44:45], v[160:161]
	v_pk_mul_f32 v[162:163], v[46:47], v[162:163]
	v_pk_mul_f32 v[164:165], v[36:37], v[164:165]
	v_pk_mul_f32 v[166:167], v[38:39], v[166:167]
	v_pk_mul_f32 v[48:49], v[48:49], v[160:161]
	v_pk_mul_f32 v[50:51], v[50:51], v[162:163]
	v_pk_mul_f32 v[40:41], v[40:41], v[164:165]
	v_pk_mul_f32 v[42:43], v[42:43], v[166:167]
	v_cvt_pk_bf16_f32 v168, v48, v49
	v_cvt_pk_bf16_f32 v169, v50, v51
	v_cvt_pk_bf16_f32 v170, v40, v41
	v_cvt_pk_bf16_f32 v171, v42, v43
	global_store_dwordx4 v[180:181], v[168:171], off
	v_pk_mul_f32 v[28:29], v[134:135], v[28:29] op_sel_hi:[0,1]
	v_pk_mul_f32 v[30:31], v[134:135], v[30:31] op_sel_hi:[0,1]
	v_pk_mul_f32 v[20:21], v[134:135], v[20:21] op_sel_hi:[0,1]
	v_pk_mul_f32 v[22:23], v[134:135], v[22:23] op_sel_hi:[0,1]
	v_pk_mul_f32 v[32:33], v[134:135], v[32:33] op_sel_hi:[0,1]
	v_pk_mul_f32 v[34:35], v[134:135], v[34:35] op_sel_hi:[0,1]
	v_pk_mul_f32 v[24:25], v[134:135], v[24:25] op_sel_hi:[0,1]
	v_pk_mul_f32 v[26:27], v[134:135], v[26:27] op_sel_hi:[0,1]
	v_pk_mul_f32 v[148:149], v[136:137], v[28:29] op_sel_hi:[0,1]
	v_pk_mul_f32 v[150:151], v[136:137], v[30:31] op_sel_hi:[0,1]
	v_pk_mul_f32 v[152:153], v[136:137], v[20:21] op_sel_hi:[0,1]
	v_pk_mul_f32 v[154:155], v[136:137], v[22:23] op_sel_hi:[0,1]
	v_exp_f32_e32 v148, v148
	v_exp_f32_e32 v149, v149
	v_exp_f32_e32 v150, v150
	v_exp_f32_e32 v151, v151
	v_exp_f32_e32 v152, v152
	v_exp_f32_e32 v153, v153
	v_exp_f32_e32 v154, v154
	v_exp_f32_e32 v155, v155
	v_fmamk_f32 v172, v218, 0x3a800000, v226
	v_add_u32_e32 v176, 0xb0, v1
	v_mul_f32_e32 v173, 0x4b800000, v172
	v_cmp_gt_f32_e32 vcc, s47, v172
	v_mad_i64_i32 v[178:179], s[12:13], v176, s55, v[140:141]
	v_lshl_add_u64 v[180:181], v[178:179], 0, v[2:3]
	v_cndmask_b32_e32 v172, v172, v173, vcc
	v_rsq_f32_e32 v172, v172
	s_nop 0
	v_mul_f32_e32 v173, 0x45800000, v172
	v_cndmask_b32_e32 v174, v172, v173, vcc
	v_pk_add_f32 v[148:149], v[138:139], v[148:149] op_sel_hi:[0,1]
	v_pk_add_f32 v[150:151], v[138:139], v[150:151] op_sel_hi:[0,1]
	v_pk_add_f32 v[152:153], v[138:139], v[152:153] op_sel_hi:[0,1]
	v_pk_add_f32 v[154:155], v[138:139], v[154:155] op_sel_hi:[0,1]
	v_rcp_f32_e32 v148, v148
	v_rcp_f32_e32 v149, v149
	v_rcp_f32_e32 v150, v150
	v_rcp_f32_e32 v151, v151
	v_rcp_f32_e32 v152, v152
	v_rcp_f32_e32 v153, v153
	v_rcp_f32_e32 v154, v154
	v_rcp_f32_e32 v155, v155
	v_pk_mul_f32 v[148:149], v[28:29], v[148:149]
	v_pk_mul_f32 v[150:151], v[30:31], v[150:151]
	v_pk_mul_f32 v[152:153], v[20:21], v[152:153]
	v_pk_mul_f32 v[154:155], v[22:23], v[154:155]
	v_pk_mul_f32 v[32:33], v[32:33], v[148:149]
	v_pk_mul_f32 v[34:35], v[34:35], v[150:151]
	v_pk_mul_f32 v[24:25], v[24:25], v[152:153]
	v_pk_mul_f32 v[26:27], v[26:27], v[154:155]
	v_cvt_pk_bf16_f32 v156, v32, v33
	v_cvt_pk_bf16_f32 v157, v34, v35
	v_cvt_pk_bf16_f32 v158, v24, v25
	v_cvt_pk_bf16_f32 v159, v26, v27
	global_store_dwordx4 v[146:147], v[156:159], off
	v_pk_mul_f32 v[12:13], v[174:175], v[12:13] op_sel_hi:[0,1]
	v_pk_mul_f32 v[14:15], v[174:175], v[14:15] op_sel_hi:[0,1]
	v_pk_mul_f32 v[4:5], v[174:175], v[4:5] op_sel_hi:[0,1]
	v_pk_mul_f32 v[6:7], v[174:175], v[6:7] op_sel_hi:[0,1]
	v_pk_mul_f32 v[16:17], v[174:175], v[16:17] op_sel_hi:[0,1]
	v_pk_mul_f32 v[18:19], v[174:175], v[18:19] op_sel_hi:[0,1]
	v_pk_mul_f32 v[8:9], v[174:175], v[8:9] op_sel_hi:[0,1]
	v_pk_mul_f32 v[10:11], v[174:175], v[10:11] op_sel_hi:[0,1]
	v_pk_mul_f32 v[160:161], v[136:137], v[12:13] op_sel_hi:[0,1]
	v_pk_mul_f32 v[162:163], v[136:137], v[14:15] op_sel_hi:[0,1]
	v_pk_mul_f32 v[164:165], v[136:137], v[4:5] op_sel_hi:[0,1]
	v_pk_mul_f32 v[166:167], v[136:137], v[6:7] op_sel_hi:[0,1]
	v_exp_f32_e32 v160, v160
	v_exp_f32_e32 v161, v161
	v_exp_f32_e32 v162, v162
	v_exp_f32_e32 v163, v163
	v_exp_f32_e32 v164, v164
	v_exp_f32_e32 v165, v165
	v_exp_f32_e32 v166, v166
	v_exp_f32_e32 v167, v167
	v_pk_add_f32 v[160:161], v[138:139], v[160:161] op_sel_hi:[0,1]
	v_pk_add_f32 v[162:163], v[138:139], v[162:163] op_sel_hi:[0,1]
	v_pk_add_f32 v[164:165], v[138:139], v[164:165] op_sel_hi:[0,1]
	v_pk_add_f32 v[166:167], v[138:139], v[166:167] op_sel_hi:[0,1]
	v_rcp_f32_e32 v160, v160
	v_rcp_f32_e32 v161, v161
	v_rcp_f32_e32 v162, v162
	v_rcp_f32_e32 v163, v163
	v_rcp_f32_e32 v164, v164
	v_rcp_f32_e32 v165, v165
	v_rcp_f32_e32 v166, v166
	v_rcp_f32_e32 v167, v167
	v_pk_mul_f32 v[160:161], v[12:13], v[160:161]
	v_pk_mul_f32 v[162:163], v[14:15], v[162:163]
	v_pk_mul_f32 v[164:165], v[4:5], v[164:165]
	v_pk_mul_f32 v[166:167], v[6:7], v[166:167]
	v_pk_mul_f32 v[16:17], v[16:17], v[160:161]
	v_pk_mul_f32 v[18:19], v[18:19], v[162:163]
	v_pk_mul_f32 v[8:9], v[8:9], v[164:165]
	v_pk_mul_f32 v[10:11], v[10:11], v[166:167]
	v_cvt_pk_bf16_f32 v168, v16, v17
	v_cvt_pk_bf16_f32 v169, v18, v19
	v_cvt_pk_bf16_f32 v170, v8, v9
	v_cvt_pk_bf16_f32 v171, v10, v11
	global_store_dwordx4 v[180:181], v[168:171], off

.LBB0_4161:
	s_waitcnt vmcnt(6)
	v_readlane_b32 s8, v255, 18
	v_readlane_b32 s9, v255, 19
	v_lshl_or_b32 v2, s22, 7, v221
	v_lshl_add_u32 v1, s20, 8, v219
	v_ashrrev_i32_e32 v3, 31, v2
	v_mov_b64_e32 v[140:141], s[8:9]
	v_mov_b32_e32 v136, 0xbfb8aa3b
	v_mov_b32_e32 v138, 1.0
	v_lshlrev_b64 v[2:3], 1, v[2:3]
	v_fmamk_f32 v132, v233, 0x3a800000, v226
	v_mul_f32_e32 v133, 0x4b800000, v132
	v_cmp_gt_f32_e32 vcc, s50, v132
	v_mad_i64_i32 v[144:145], s[8:9], v1, s51, v[140:141]
	v_lshl_add_u64 v[146:147], v[144:145], 0, v[2:3]
	v_cndmask_b32_e32 v132, v132, v133, vcc
	v_rsq_f32_e32 v132, v132
	s_nop 0
	v_mul_f32_e32 v133, 0x45800000, v132
	v_cndmask_b32_e32 v134, v132, v133, vcc
	v_pk_mul_f32 v[124:125], v[134:135], v[124:125] op_sel_hi:[0,1]
	v_pk_mul_f32 v[126:127], v[134:135], v[126:127] op_sel_hi:[0,1]
	v_pk_mul_f32 v[116:117], v[134:135], v[116:117] op_sel_hi:[0,1]
	v_pk_mul_f32 v[118:119], v[134:135], v[118:119] op_sel_hi:[0,1]
	v_pk_mul_f32 v[128:129], v[134:135], v[128:129] op_sel_hi:[0,1]
	v_pk_mul_f32 v[130:131], v[134:135], v[130:131] op_sel_hi:[0,1]
	v_pk_mul_f32 v[120:121], v[134:135], v[120:121] op_sel_hi:[0,1]
	v_pk_mul_f32 v[122:123], v[134:135], v[122:123] op_sel_hi:[0,1]
	v_pk_mul_f32 v[148:149], v[136:137], v[124:125] op_sel_hi:[0,1]
	v_pk_mul_f32 v[150:151], v[136:137], v[126:127] op_sel_hi:[0,1]
	v_pk_mul_f32 v[152:153], v[136:137], v[116:117] op_sel_hi:[0,1]
	v_pk_mul_f32 v[154:155], v[136:137], v[118:119] op_sel_hi:[0,1]
	v_exp_f32_e32 v148, v148
	v_exp_f32_e32 v149, v149
	v_exp_f32_e32 v150, v150
	v_exp_f32_e32 v151, v151
	v_exp_f32_e32 v152, v152
	v_exp_f32_e32 v153, v153
	v_exp_f32_e32 v154, v154
	v_exp_f32_e32 v155, v155
	v_fmamk_f32 v172, v232, 0x3a800000, v226
	v_or_b32_e32 v176, 16, v1
	v_mul_f32_e32 v173, 0x4b800000, v172
	v_cmp_gt_f32_e32 vcc, s50, v172
	v_mad_i64_i32 v[178:179], s[8:9], v176, s51, v[140:141]
	v_lshl_add_u64 v[180:181], v[178:179], 0, v[2:3]
	v_cndmask_b32_e32 v172, v172, v173, vcc
	v_rsq_f32_e32 v172, v172
	s_nop 0
	v_mul_f32_e32 v173, 0x45800000, v172
	v_cndmask_b32_e32 v174, v172, v173, vcc
	v_pk_add_f32 v[148:149], v[138:139], v[148:149] op_sel_hi:[0,1]
	v_pk_add_f32 v[150:151], v[138:139], v[150:151] op_sel_hi:[0,1]
	v_pk_add_f32 v[152:153], v[138:139], v[152:153] op_sel_hi:[0,1]
	v_pk_add_f32 v[154:155], v[138:139], v[154:155] op_sel_hi:[0,1]
	v_rcp_f32_e32 v148, v148
	v_rcp_f32_e32 v149, v149
	v_rcp_f32_e32 v150, v150
	v_rcp_f32_e32 v151, v151
	v_rcp_f32_e32 v152, v152
	v_rcp_f32_e32 v153, v153
	v_rcp_f32_e32 v154, v154
	v_rcp_f32_e32 v155, v155
	v_pk_mul_f32 v[148:149], v[124:125], v[148:149]
	v_pk_mul_f32 v[150:151], v[126:127], v[150:151]
	v_pk_mul_f32 v[152:153], v[116:117], v[152:153]
	v_pk_mul_f32 v[154:155], v[118:119], v[154:155]
	v_pk_mul_f32 v[128:129], v[128:129], v[148:149]
	v_pk_mul_f32 v[130:131], v[130:131], v[150:151]
	v_pk_mul_f32 v[120:121], v[120:121], v[152:153]
	v_pk_mul_f32 v[122:123], v[122:123], v[154:155]
	v_cvt_pk_bf16_f32 v156, v128, v129
	v_cvt_pk_bf16_f32 v157, v130, v131
	v_cvt_pk_bf16_f32 v158, v120, v121
	v_cvt_pk_bf16_f32 v159, v122, v123
	global_store_dwordx4 v[146:147], v[156:159], off
	v_pk_mul_f32 v[108:109], v[174:175], v[108:109] op_sel_hi:[0,1]
	v_pk_mul_f32 v[110:111], v[174:175], v[110:111] op_sel_hi:[0,1]
	v_pk_mul_f32 v[100:101], v[174:175], v[100:101] op_sel_hi:[0,1]
	v_pk_mul_f32 v[102:103], v[174:175], v[102:103] op_sel_hi:[0,1]
	v_pk_mul_f32 v[112:113], v[174:175], v[112:113] op_sel_hi:[0,1]
	v_pk_mul_f32 v[114:115], v[174:175], v[114:115] op_sel_hi:[0,1]
	v_pk_mul_f32 v[104:105], v[174:175], v[104:105] op_sel_hi:[0,1]
	v_pk_mul_f32 v[106:107], v[174:175], v[106:107] op_sel_hi:[0,1]
	v_pk_mul_f32 v[160:161], v[136:137], v[108:109] op_sel_hi:[0,1]
	v_pk_mul_f32 v[162:163], v[136:137], v[110:111] op_sel_hi:[0,1]
	v_pk_mul_f32 v[164:165], v[136:137], v[100:101] op_sel_hi:[0,1]
	v_pk_mul_f32 v[166:167], v[136:137], v[102:103] op_sel_hi:[0,1]
	v_exp_f32_e32 v160, v160
	v_exp_f32_e32 v161, v161
	v_exp_f32_e32 v162, v162
	v_exp_f32_e32 v163, v163
	v_exp_f32_e32 v164, v164
	v_exp_f32_e32 v165, v165
	v_exp_f32_e32 v166, v166
	v_exp_f32_e32 v167, v167
	v_fmamk_f32 v132, v231, 0x3a800000, v226
	v_or_b32_e32 v142, 32, v1
	v_mul_f32_e32 v133, 0x4b800000, v132
	v_cmp_gt_f32_e32 vcc, s50, v132
	v_mad_i64_i32 v[144:145], s[8:9], v142, s51, v[140:141]
	v_lshl_add_u64 v[146:147], v[144:145], 0, v[2:3]
	v_cndmask_b32_e32 v132, v132, v133, vcc
	v_rsq_f32_e32 v132, v132
	s_nop 0
	v_mul_f32_e32 v133, 0x45800000, v132
	v_cndmask_b32_e32 v134, v132, v133, vcc
	v_pk_add_f32 v[160:161], v[138:139], v[160:161] op_sel_hi:[0,1]
	v_pk_add_f32 v[162:163], v[138:139], v[162:163] op_sel_hi:[0,1]
	v_pk_add_f32 v[164:165], v[138:139], v[164:165] op_sel_hi:[0,1]
	v_pk_add_f32 v[166:167], v[138:139], v[166:167] op_sel_hi:[0,1]
	v_rcp_f32_e32 v160, v160
	v_rcp_f32_e32 v161, v161
	v_rcp_f32_e32 v162, v162
	v_rcp_f32_e32 v163, v163
	v_rcp_f32_e32 v164, v164
	v_rcp_f32_e32 v165, v165
	v_rcp_f32_e32 v166, v166
	v_rcp_f32_e32 v167, v167
	v_pk_mul_f32 v[160:161], v[108:109], v[160:161]
	v_pk_mul_f32 v[162:163], v[110:111], v[162:163]
	v_pk_mul_f32 v[164:165], v[100:101], v[164:165]
	v_pk_mul_f32 v[166:167], v[102:103], v[166:167]
	v_pk_mul_f32 v[112:113], v[112:113], v[160:161]
	v_pk_mul_f32 v[114:115], v[114:115], v[162:163]
	v_pk_mul_f32 v[104:105], v[104:105], v[164:165]
	v_pk_mul_f32 v[106:107], v[106:107], v[166:167]
	v_cvt_pk_bf16_f32 v168, v112, v113
	v_cvt_pk_bf16_f32 v169, v114, v115
	v_cvt_pk_bf16_f32 v170, v104, v105
	v_cvt_pk_bf16_f32 v171, v106, v107
	global_store_dwordx4 v[180:181], v[168:171], off
	v_pk_mul_f32 v[92:93], v[134:135], v[92:93] op_sel_hi:[0,1]
	v_pk_mul_f32 v[94:95], v[134:135], v[94:95] op_sel_hi:[0,1]
	v_pk_mul_f32 v[84:85], v[134:135], v[84:85] op_sel_hi:[0,1]
	v_pk_mul_f32 v[86:87], v[134:135], v[86:87] op_sel_hi:[0,1]
	v_pk_mul_f32 v[96:97], v[134:135], v[96:97] op_sel_hi:[0,1]
	v_pk_mul_f32 v[98:99], v[134:135], v[98:99] op_sel_hi:[0,1]
	v_pk_mul_f32 v[88:89], v[134:135], v[88:89] op_sel_hi:[0,1]
	v_pk_mul_f32 v[90:91], v[134:135], v[90:91] op_sel_hi:[0,1]
	v_pk_mul_f32 v[148:149], v[136:137], v[92:93] op_sel_hi:[0,1]
	v_pk_mul_f32 v[150:151], v[136:137], v[94:95] op_sel_hi:[0,1]
	v_pk_mul_f32 v[152:153], v[136:137], v[84:85] op_sel_hi:[0,1]
	v_pk_mul_f32 v[154:155], v[136:137], v[86:87] op_sel_hi:[0,1]
	v_exp_f32_e32 v148, v148
	v_exp_f32_e32 v149, v149
	v_exp_f32_e32 v150, v150
	v_exp_f32_e32 v151, v151
	v_exp_f32_e32 v152, v152
	v_exp_f32_e32 v153, v153
	v_exp_f32_e32 v154, v154
	v_exp_f32_e32 v155, v155
	v_fmamk_f32 v172, v230, 0x3a800000, v226
	v_or_b32_e32 v176, 48, v1
	v_mul_f32_e32 v173, 0x4b800000, v172
	v_cmp_gt_f32_e32 vcc, s50, v172
	v_mad_i64_i32 v[178:179], s[8:9], v176, s51, v[140:141]
	v_lshl_add_u64 v[180:181], v[178:179], 0, v[2:3]
	v_cndmask_b32_e32 v172, v172, v173, vcc
	v_rsq_f32_e32 v172, v172
	s_nop 0
	v_mul_f32_e32 v173, 0x45800000, v172
	v_cndmask_b32_e32 v174, v172, v173, vcc
	v_pk_add_f32 v[148:149], v[138:139], v[148:149] op_sel_hi:[0,1]
	v_pk_add_f32 v[150:151], v[138:139], v[150:151] op_sel_hi:[0,1]
	v_pk_add_f32 v[152:153], v[138:139], v[152:153] op_sel_hi:[0,1]
	v_pk_add_f32 v[154:155], v[138:139], v[154:155] op_sel_hi:[0,1]
	v_rcp_f32_e32 v148, v148
	v_rcp_f32_e32 v149, v149
	v_rcp_f32_e32 v150, v150
	v_rcp_f32_e32 v151, v151
	v_rcp_f32_e32 v152, v152
	v_rcp_f32_e32 v153, v153
	v_rcp_f32_e32 v154, v154
	v_rcp_f32_e32 v155, v155
	v_pk_mul_f32 v[148:149], v[92:93], v[148:149]
	v_pk_mul_f32 v[150:151], v[94:95], v[150:151]
	v_pk_mul_f32 v[152:153], v[84:85], v[152:153]
	v_pk_mul_f32 v[154:155], v[86:87], v[154:155]
	v_pk_mul_f32 v[96:97], v[96:97], v[148:149]
	v_pk_mul_f32 v[98:99], v[98:99], v[150:151]
	v_pk_mul_f32 v[88:89], v[88:89], v[152:153]
	v_pk_mul_f32 v[90:91], v[90:91], v[154:155]
	v_cvt_pk_bf16_f32 v156, v96, v97
	v_cvt_pk_bf16_f32 v157, v98, v99
	v_cvt_pk_bf16_f32 v158, v88, v89
	v_cvt_pk_bf16_f32 v159, v90, v91
	global_store_dwordx4 v[146:147], v[156:159], off
	v_pk_mul_f32 v[76:77], v[174:175], v[76:77] op_sel_hi:[0,1]
	v_pk_mul_f32 v[78:79], v[174:175], v[78:79] op_sel_hi:[0,1]
	v_pk_mul_f32 v[72:73], v[174:175], v[72:73] op_sel_hi:[0,1]
	v_pk_mul_f32 v[74:75], v[174:175], v[74:75] op_sel_hi:[0,1]
	v_pk_mul_f32 v[80:81], v[174:175], v[80:81] op_sel_hi:[0,1]
	v_pk_mul_f32 v[82:83], v[174:175], v[82:83] op_sel_hi:[0,1]
	v_pk_mul_f32 v[68:69], v[174:175], v[68:69] op_sel_hi:[0,1]
	v_pk_mul_f32 v[70:71], v[174:175], v[70:71] op_sel_hi:[0,1]
	v_pk_mul_f32 v[160:161], v[136:137], v[76:77] op_sel_hi:[0,1]
	v_pk_mul_f32 v[162:163], v[136:137], v[78:79] op_sel_hi:[0,1]
	v_pk_mul_f32 v[164:165], v[136:137], v[72:73] op_sel_hi:[0,1]
	v_pk_mul_f32 v[166:167], v[136:137], v[74:75] op_sel_hi:[0,1]
	v_exp_f32_e32 v160, v160
	v_exp_f32_e32 v161, v161
	v_exp_f32_e32 v162, v162
	v_exp_f32_e32 v163, v163
	v_exp_f32_e32 v164, v164
	v_exp_f32_e32 v165, v165
	v_exp_f32_e32 v166, v166
	v_exp_f32_e32 v167, v167
	v_pk_add_f32 v[160:161], v[138:139], v[160:161] op_sel_hi:[0,1]
	v_pk_add_f32 v[162:163], v[138:139], v[162:163] op_sel_hi:[0,1]
	v_pk_add_f32 v[164:165], v[138:139], v[164:165] op_sel_hi:[0,1]
	v_pk_add_f32 v[166:167], v[138:139], v[166:167] op_sel_hi:[0,1]
	v_rcp_f32_e32 v160, v160
	v_rcp_f32_e32 v161, v161
	v_rcp_f32_e32 v162, v162
	v_rcp_f32_e32 v163, v163
	v_rcp_f32_e32 v164, v164
	v_rcp_f32_e32 v165, v165
	v_rcp_f32_e32 v166, v166
	v_rcp_f32_e32 v167, v167
	v_pk_mul_f32 v[160:161], v[76:77], v[160:161]
	v_pk_mul_f32 v[162:163], v[78:79], v[162:163]
	v_pk_mul_f32 v[164:165], v[72:73], v[164:165]
	v_pk_mul_f32 v[166:167], v[74:75], v[166:167]
	v_pk_mul_f32 v[80:81], v[80:81], v[160:161]
	v_pk_mul_f32 v[82:83], v[82:83], v[162:163]
	v_pk_mul_f32 v[68:69], v[68:69], v[164:165]
	v_pk_mul_f32 v[70:71], v[70:71], v[166:167]
	v_cvt_pk_bf16_f32 v168, v80, v81
	v_cvt_pk_bf16_f32 v169, v82, v83
	v_cvt_pk_bf16_f32 v170, v68, v69
	v_cvt_pk_bf16_f32 v171, v70, v71
	global_store_dwordx4 v[180:181], v[168:171], off
	s_cmp_eq_u32 s20, 64
	s_cbranch_scc1 .LBB0_4163
	v_fmamk_f32 v132, v229, 0x3a800000, v226
	v_add_u32_e32 v142, 0x80, v1
	v_mul_f32_e32 v133, 0x4b800000, v132
	v_cmp_gt_f32_e32 vcc, s50, v132
	v_mad_i64_i32 v[144:145], s[8:9], v142, s51, v[140:141]
	v_lshl_add_u64 v[146:147], v[144:145], 0, v[2:3]
	v_cndmask_b32_e32 v132, v132, v133, vcc
	v_rsq_f32_e32 v132, v132
	s_nop 0
	v_mul_f32_e32 v133, 0x45800000, v132
	v_cndmask_b32_e32 v134, v132, v133, vcc
	v_pk_mul_f32 v[60:61], v[134:135], v[60:61] op_sel_hi:[0,1]
	v_pk_mul_f32 v[62:63], v[134:135], v[62:63] op_sel_hi:[0,1]
	v_pk_mul_f32 v[52:53], v[134:135], v[52:53] op_sel_hi:[0,1]
	v_pk_mul_f32 v[54:55], v[134:135], v[54:55] op_sel_hi:[0,1]
	v_pk_mul_f32 v[64:65], v[134:135], v[64:65] op_sel_hi:[0,1]
	v_pk_mul_f32 v[66:67], v[134:135], v[66:67] op_sel_hi:[0,1]
	v_pk_mul_f32 v[56:57], v[134:135], v[56:57] op_sel_hi:[0,1]
	v_pk_mul_f32 v[58:59], v[134:135], v[58:59] op_sel_hi:[0,1]
	v_pk_mul_f32 v[148:149], v[136:137], v[60:61] op_sel_hi:[0,1]
	v_pk_mul_f32 v[150:151], v[136:137], v[62:63] op_sel_hi:[0,1]
	v_pk_mul_f32 v[152:153], v[136:137], v[52:53] op_sel_hi:[0,1]
	v_pk_mul_f32 v[154:155], v[136:137], v[54:55] op_sel_hi:[0,1]
	v_exp_f32_e32 v148, v148
	v_exp_f32_e32 v149, v149
	v_exp_f32_e32 v150, v150
	v_exp_f32_e32 v151, v151
	v_exp_f32_e32 v152, v152
	v_exp_f32_e32 v153, v153
	v_exp_f32_e32 v154, v154
	v_exp_f32_e32 v155, v155
	v_fmamk_f32 v172, v228, 0x3a800000, v226
	v_add_u32_e32 v176, 0x90, v1
	v_mul_f32_e32 v173, 0x4b800000, v172
	v_cmp_gt_f32_e32 vcc, s50, v172
	v_mad_i64_i32 v[178:179], s[8:9], v176, s51, v[140:141]
	v_lshl_add_u64 v[180:181], v[178:179], 0, v[2:3]
	v_cndmask_b32_e32 v172, v172, v173, vcc
	v_rsq_f32_e32 v172, v172
	s_nop 0
	v_mul_f32_e32 v173, 0x45800000, v172
	v_cndmask_b32_e32 v174, v172, v173, vcc
	v_pk_add_f32 v[148:149], v[138:139], v[148:149] op_sel_hi:[0,1]
	v_pk_add_f32 v[150:151], v[138:139], v[150:151] op_sel_hi:[0,1]
	v_pk_add_f32 v[152:153], v[138:139], v[152:153] op_sel_hi:[0,1]
	v_pk_add_f32 v[154:155], v[138:139], v[154:155] op_sel_hi:[0,1]
	v_rcp_f32_e32 v148, v148
	v_rcp_f32_e32 v149, v149
	v_rcp_f32_e32 v150, v150
	v_rcp_f32_e32 v151, v151
	v_rcp_f32_e32 v152, v152
	v_rcp_f32_e32 v153, v153
	v_rcp_f32_e32 v154, v154
	v_rcp_f32_e32 v155, v155
	v_pk_mul_f32 v[148:149], v[60:61], v[148:149]
	v_pk_mul_f32 v[150:151], v[62:63], v[150:151]
	v_pk_mul_f32 v[152:153], v[52:53], v[152:153]
	v_pk_mul_f32 v[154:155], v[54:55], v[154:155]
	v_pk_mul_f32 v[64:65], v[64:65], v[148:149]
	v_pk_mul_f32 v[66:67], v[66:67], v[150:151]
	v_pk_mul_f32 v[56:57], v[56:57], v[152:153]
	v_pk_mul_f32 v[58:59], v[58:59], v[154:155]
	v_cvt_pk_bf16_f32 v156, v64, v65
	v_cvt_pk_bf16_f32 v157, v66, v67
	v_cvt_pk_bf16_f32 v158, v56, v57
	v_cvt_pk_bf16_f32 v159, v58, v59
	global_store_dwordx4 v[146:147], v[156:159], off
	v_pk_mul_f32 v[44:45], v[174:175], v[44:45] op_sel_hi:[0,1]
	v_pk_mul_f32 v[46:47], v[174:175], v[46:47] op_sel_hi:[0,1]
	v_pk_mul_f32 v[36:37], v[174:175], v[36:37] op_sel_hi:[0,1]
	v_pk_mul_f32 v[38:39], v[174:175], v[38:39] op_sel_hi:[0,1]
	v_pk_mul_f32 v[48:49], v[174:175], v[48:49] op_sel_hi:[0,1]
	v_pk_mul_f32 v[50:51], v[174:175], v[50:51] op_sel_hi:[0,1]
	v_pk_mul_f32 v[40:41], v[174:175], v[40:41] op_sel_hi:[0,1]
	v_pk_mul_f32 v[42:43], v[174:175], v[42:43] op_sel_hi:[0,1]
	v_pk_mul_f32 v[160:161], v[136:137], v[44:45] op_sel_hi:[0,1]
	v_pk_mul_f32 v[162:163], v[136:137], v[46:47] op_sel_hi:[0,1]
	v_pk_mul_f32 v[164:165], v[136:137], v[36:37] op_sel_hi:[0,1]
	v_pk_mul_f32 v[166:167], v[136:137], v[38:39] op_sel_hi:[0,1]
	v_exp_f32_e32 v160, v160
	v_exp_f32_e32 v161, v161
	v_exp_f32_e32 v162, v162
	v_exp_f32_e32 v163, v163
	v_exp_f32_e32 v164, v164
	v_exp_f32_e32 v165, v165
	v_exp_f32_e32 v166, v166
	v_exp_f32_e32 v167, v167
	v_fmamk_f32 v132, v227, 0x3a800000, v226
	v_add_u32_e32 v142, 0xa0, v1
	v_mul_f32_e32 v133, 0x4b800000, v132
	v_cmp_gt_f32_e32 vcc, s50, v132
	v_mad_i64_i32 v[144:145], s[8:9], v142, s51, v[140:141]
	v_lshl_add_u64 v[146:147], v[144:145], 0, v[2:3]
	v_cndmask_b32_e32 v132, v132, v133, vcc
	v_rsq_f32_e32 v132, v132
	s_nop 0
	v_mul_f32_e32 v133, 0x45800000, v132
	v_cndmask_b32_e32 v134, v132, v133, vcc
	v_pk_add_f32 v[160:161], v[138:139], v[160:161] op_sel_hi:[0,1]
	v_pk_add_f32 v[162:163], v[138:139], v[162:163] op_sel_hi:[0,1]
	v_pk_add_f32 v[164:165], v[138:139], v[164:165] op_sel_hi:[0,1]
	v_pk_add_f32 v[166:167], v[138:139], v[166:167] op_sel_hi:[0,1]
	v_rcp_f32_e32 v160, v160
	v_rcp_f32_e32 v161, v161
	v_rcp_f32_e32 v162, v162
	v_rcp_f32_e32 v163, v163
	v_rcp_f32_e32 v164, v164
	v_rcp_f32_e32 v165, v165
	v_rcp_f32_e32 v166, v166
	v_rcp_f32_e32 v167, v167
	v_pk_mul_f32 v[160:161], v[44:45], v[160:161]
	v_pk_mul_f32 v[162:163], v[46:47], v[162:163]
	v_pk_mul_f32 v[164:165], v[36:37], v[164:165]
	v_pk_mul_f32 v[166:167], v[38:39], v[166:167]
	v_pk_mul_f32 v[48:49], v[48:49], v[160:161]
	v_pk_mul_f32 v[50:51], v[50:51], v[162:163]
	v_pk_mul_f32 v[40:41], v[40:41], v[164:165]
	v_pk_mul_f32 v[42:43], v[42:43], v[166:167]
	v_cvt_pk_bf16_f32 v168, v48, v49
	v_cvt_pk_bf16_f32 v169, v50, v51
	v_cvt_pk_bf16_f32 v170, v40, v41
	v_cvt_pk_bf16_f32 v171, v42, v43
	global_store_dwordx4 v[180:181], v[168:171], off
	v_pk_mul_f32 v[28:29], v[134:135], v[28:29] op_sel_hi:[0,1]
	v_pk_mul_f32 v[30:31], v[134:135], v[30:31] op_sel_hi:[0,1]
	v_pk_mul_f32 v[20:21], v[134:135], v[20:21] op_sel_hi:[0,1]
	v_pk_mul_f32 v[22:23], v[134:135], v[22:23] op_sel_hi:[0,1]
	v_pk_mul_f32 v[32:33], v[134:135], v[32:33] op_sel_hi:[0,1]
	v_pk_mul_f32 v[34:35], v[134:135], v[34:35] op_sel_hi:[0,1]
	v_pk_mul_f32 v[24:25], v[134:135], v[24:25] op_sel_hi:[0,1]
	v_pk_mul_f32 v[26:27], v[134:135], v[26:27] op_sel_hi:[0,1]
	v_pk_mul_f32 v[148:149], v[136:137], v[28:29] op_sel_hi:[0,1]
	v_pk_mul_f32 v[150:151], v[136:137], v[30:31] op_sel_hi:[0,1]
	v_pk_mul_f32 v[152:153], v[136:137], v[20:21] op_sel_hi:[0,1]
	v_pk_mul_f32 v[154:155], v[136:137], v[22:23] op_sel_hi:[0,1]
	v_exp_f32_e32 v148, v148
	v_exp_f32_e32 v149, v149
	v_exp_f32_e32 v150, v150
	v_exp_f32_e32 v151, v151
	v_exp_f32_e32 v152, v152
	v_exp_f32_e32 v153, v153
	v_exp_f32_e32 v154, v154
	v_exp_f32_e32 v155, v155
	v_fmamk_f32 v172, v218, 0x3a800000, v226
	v_add_u32_e32 v176, 0xb0, v1
	v_mul_f32_e32 v173, 0x4b800000, v172
	v_cmp_gt_f32_e32 vcc, s50, v172
	v_mad_i64_i32 v[178:179], s[8:9], v176, s51, v[140:141]
	v_lshl_add_u64 v[180:181], v[178:179], 0, v[2:3]
	v_cndmask_b32_e32 v172, v172, v173, vcc
	v_rsq_f32_e32 v172, v172
	s_nop 0
	v_mul_f32_e32 v173, 0x45800000, v172
	v_cndmask_b32_e32 v174, v172, v173, vcc
	v_pk_add_f32 v[148:149], v[138:139], v[148:149] op_sel_hi:[0,1]
	v_pk_add_f32 v[150:151], v[138:139], v[150:151] op_sel_hi:[0,1]
	v_pk_add_f32 v[152:153], v[138:139], v[152:153] op_sel_hi:[0,1]
	v_pk_add_f32 v[154:155], v[138:139], v[154:155] op_sel_hi:[0,1]
	v_rcp_f32_e32 v148, v148
	v_rcp_f32_e32 v149, v149
	v_rcp_f32_e32 v150, v150
	v_rcp_f32_e32 v151, v151
	v_rcp_f32_e32 v152, v152
	v_rcp_f32_e32 v153, v153
	v_rcp_f32_e32 v154, v154
	v_rcp_f32_e32 v155, v155
	v_pk_mul_f32 v[148:149], v[28:29], v[148:149]
	v_pk_mul_f32 v[150:151], v[30:31], v[150:151]
	v_pk_mul_f32 v[152:153], v[20:21], v[152:153]
	v_pk_mul_f32 v[154:155], v[22:23], v[154:155]
	v_pk_mul_f32 v[32:33], v[32:33], v[148:149]
	v_pk_mul_f32 v[34:35], v[34:35], v[150:151]
	v_pk_mul_f32 v[24:25], v[24:25], v[152:153]
	v_pk_mul_f32 v[26:27], v[26:27], v[154:155]
	v_cvt_pk_bf16_f32 v156, v32, v33
	v_cvt_pk_bf16_f32 v157, v34, v35
	v_cvt_pk_bf16_f32 v158, v24, v25
	v_cvt_pk_bf16_f32 v159, v26, v27
	global_store_dwordx4 v[146:147], v[156:159], off
	v_pk_mul_f32 v[12:13], v[174:175], v[12:13] op_sel_hi:[0,1]
	v_pk_mul_f32 v[14:15], v[174:175], v[14:15] op_sel_hi:[0,1]
	v_pk_mul_f32 v[4:5], v[174:175], v[4:5] op_sel_hi:[0,1]
	v_pk_mul_f32 v[6:7], v[174:175], v[6:7] op_sel_hi:[0,1]
	v_pk_mul_f32 v[16:17], v[174:175], v[16:17] op_sel_hi:[0,1]
	v_pk_mul_f32 v[18:19], v[174:175], v[18:19] op_sel_hi:[0,1]
	v_pk_mul_f32 v[8:9], v[174:175], v[8:9] op_sel_hi:[0,1]
	v_pk_mul_f32 v[10:11], v[174:175], v[10:11] op_sel_hi:[0,1]
	v_pk_mul_f32 v[160:161], v[136:137], v[12:13] op_sel_hi:[0,1]
	v_pk_mul_f32 v[162:163], v[136:137], v[14:15] op_sel_hi:[0,1]
	v_pk_mul_f32 v[164:165], v[136:137], v[4:5] op_sel_hi:[0,1]
	v_pk_mul_f32 v[166:167], v[136:137], v[6:7] op_sel_hi:[0,1]
	v_exp_f32_e32 v160, v160
	v_exp_f32_e32 v161, v161
	v_exp_f32_e32 v162, v162
	v_exp_f32_e32 v163, v163
	v_exp_f32_e32 v164, v164
	v_exp_f32_e32 v165, v165
	v_exp_f32_e32 v166, v166
	v_exp_f32_e32 v167, v167
	v_pk_add_f32 v[160:161], v[138:139], v[160:161] op_sel_hi:[0,1]
	v_pk_add_f32 v[162:163], v[138:139], v[162:163] op_sel_hi:[0,1]
	v_pk_add_f32 v[164:165], v[138:139], v[164:165] op_sel_hi:[0,1]
	v_pk_add_f32 v[166:167], v[138:139], v[166:167] op_sel_hi:[0,1]
	v_rcp_f32_e32 v160, v160
	v_rcp_f32_e32 v161, v161
	v_rcp_f32_e32 v162, v162
	v_rcp_f32_e32 v163, v163
	v_rcp_f32_e32 v164, v164
	v_rcp_f32_e32 v165, v165
	v_rcp_f32_e32 v166, v166
	v_rcp_f32_e32 v167, v167
	v_pk_mul_f32 v[160:161], v[12:13], v[160:161]
	v_pk_mul_f32 v[162:163], v[14:15], v[162:163]
	v_pk_mul_f32 v[164:165], v[4:5], v[164:165]
	v_pk_mul_f32 v[166:167], v[6:7], v[166:167]
	v_pk_mul_f32 v[16:17], v[16:17], v[160:161]
	v_pk_mul_f32 v[18:19], v[18:19], v[162:163]
	v_pk_mul_f32 v[8:9], v[8:9], v[164:165]
	v_pk_mul_f32 v[10:11], v[10:11], v[166:167]
	v_cvt_pk_bf16_f32 v168, v16, v17
	v_cvt_pk_bf16_f32 v169, v18, v19
	v_cvt_pk_bf16_f32 v170, v8, v9
	v_cvt_pk_bf16_f32 v171, v10, v11
	global_store_dwordx4 v[180:181], v[168:171], off
